# epilogue load prefetch: all branch-GEMM gate vectors and residual-GEMM Xin vectors issued up front into dead fragment registers instead of serialized load-wait per row; plus earlier sumsq/norm_g hoist
# speedup vs baseline: 1.0323x; 1.0222x over previous
; __device__ __forceinline__ float sigm(float x) { return rcpf_(1.f + __expf(-x)); }
; __device__ __forceinline__ void unpack8(u32x4 w, float* e) { e[0] = lo_bf(w.x); e[1] = hi_bf(w.x); e[2] = lo_bf(w.y); e[3] = hi_bf(w.y); e[4] = lo_bf(w.z); e[5] = hi_bf(w.z); e[6] = lo_bf(w.w); e[7] = hi_bf(w.w); }
;     __device__ __forceinline__ void operator()(const f32x4 (&acc)[2][2][4][2], const Unit& u, int wr, int wc, int fr, int fq) const {
;         const int row0 = u.pm * 256 + wr * 64 + fr, colt = u.pn * 256 + wc * 32 + 8 * fq;
; #pragma unroll
;         for (int ai = 0; ai < 2; ++ai)
; #pragma unroll
;             for (int m = 0; m < 4; ++m) {
;                 const int row = row0 + ai * 128 + m * 16;
; #pragma unroll
;                 for (int bj = 0; bj < 2; ++bj) {
;                     const int col = colt + bj * 128;
;                     const u32x4 gw = *(const u32x4*)(P + (size_t)row * NIN + C_GM + u.z * 1024 + col);
;                     float gt[8]; unpack8(gw, gt);
;                     f32x4 v0 = acc[ai][bj][m][0], v1 = acc[ai][bj][m][1];
; #pragma unroll
;                     for (int j = 0; j < 4; ++j) { v0[j] *= sigm(gt[j]); v1[j] *= sigm(gt[4 + j]); }
;                     float* tp = tmp + (size_t)row * 1024 + col;
;                     if (u.z > 0) { v0 += *(const f32x4*)tp; v1 += *(const f32x4*)(tp + 4); }
;                     if (u.z < 2) { *(f32x4*)tp = v0; *(f32x4*)(tp + 4) = v1; }
.LBB0_116:
	v_lshl_add_u32 v142, s87, 8, v150
	v_mov_b64_e32 v[144:145], s[12:13]
	s_lshl_b32 s38, s85, 10
	v_lshl_or_b32 v140, s86, 8, v152
	v_mad_i64_i32 v[144:145], s[6:7], v142, s43, v[144:145]
	s_ashr_i32 s39, s38, 31
	v_lshl_add_u64 v[144:145], s[38:39], 1, v[144:145]
	v_ashrrev_i32_e32 v141, 31, v140
	v_lshl_add_u64 v[144:145], v[140:141], 1, v[144:145]
	v_add_co_u32_e32 v146, vcc, 0x4000, v144
	v_ashrrev_i32_e32 v143, 31, v142
	s_nop 0
	v_addc_co_u32_e32 v147, vcc, 0, v145, vcc
	global_load_dwordx4 v[196:199], v[146:147], off offset:256
	s_mov_b32 s99, 0
	s_mov_b32 s98, 0x58000
	v_lshl_add_u64 v[162:163], v[146:147], 0, s[98:99]
	global_load_dwordx4 v[200:203], v[162:163], off offset:256
	global_load_dwordx4 v[162:165], v[162:163], off
	s_mov_b32 s98, 0xb0000
	v_lshl_add_u64 v[166:167], v[146:147], 0, s[98:99]
	global_load_dwordx4 v[204:207], v[166:167], off offset:256
	global_load_dwordx4 v[166:169], v[166:167], off
	s_mov_b32 s98, 0x108000
	v_lshl_add_u64 v[170:171], v[146:147], 0, s[98:99]
	global_load_dwordx4 v[208:211], v[170:171], off offset:256
	global_load_dwordx4 v[170:173], v[170:171], off
	s_mov_b32 s98, 0x2c0000
	v_lshl_add_u64 v[174:175], v[146:147], 0, s[98:99]
	global_load_dwordx4 v[212:215], v[174:175], off offset:256
	global_load_dwordx4 v[174:177], v[174:175], off
	s_mov_b32 s98, 0x318000
	v_lshl_add_u64 v[178:179], v[146:147], 0, s[98:99]
	global_load_dwordx4 v[230:233], v[178:179], off offset:256
	global_load_dwordx4 v[178:181], v[178:179], off
	s_mov_b32 s98, 0x370000
	v_lshl_add_u64 v[188:189], v[146:147], 0, s[98:99]
	global_load_dwordx4 v[248:251], v[188:189], off offset:256
	global_load_dwordx4 v[188:191], v[188:189], off
	s_mov_b32 s98, 0x3c8000
	v_lshl_add_u64 v[192:193], v[146:147], 0, s[98:99]
	global_load_dwordx4 v[192:195], v[192:193], off
	global_load_dwordx4 v[146:149], v[146:147], off
	s_cmp_gt_i32 s85, 0
	s_cselect_b64 s[8:9], -1, 0
	s_cmp_lt_i32 s85, 1
	s_waitcnt vmcnt(0)
	v_lshlrev_b32_e32 v156, 16, v147
	v_and_b32_e32 v157, 0xffff0000, v147
	v_lshlrev_b32_e32 v147, 16, v148
	v_mul_f32_e32 v147, 0xbfb8aa3b, v147
	v_exp_f32_e32 v147, v147
	v_lshlrev_b32_e32 v154, 16, v146
	v_and_b32_e32 v155, 0xffff0000, v146
	v_and_b32_e32 v158, 0xffff0000, v148
	v_add_f32_e32 v147, 1.0, v147
	v_mul_f32_e32 v146, 0xbfb8aa3b, v154
	v_rcp_f32_e32 v148, v147
	v_mul_f32_e32 v147, 0xbfb8aa3b, v155
	v_exp_f32_e32 v146, v146
	v_exp_f32_e32 v147, v147
	v_lshlrev_b32_e32 v159, 16, v149
	v_mul_f32_e32 v155, 0xbfb8aa3b, v159
	v_add_f32_e32 v146, 1.0, v146
	v_add_f32_e32 v147, 1.0, v147
	v_exp_f32_e32 v155, v155
	v_rcp_f32_e32 v146, v146
	v_rcp_f32_e32 v147, v147
	v_and_b32_e32 v160, 0xffff0000, v149
	v_add_f32_e32 v155, 1.0, v155
	v_mul_f32_e32 v149, 0xbfb8aa3b, v158
	v_mul_f32_e32 v154, 0xbfb8aa3b, v156
	v_rcp_f32_e32 v156, v155
	v_mul_f32_e32 v155, 0xbfb8aa3b, v157
	v_pk_mul_f32 v[126:127], v[126:127], v[146:147]
	v_mul_f32_e32 v146, 0xbfb8aa3b, v160
	v_exp_f32_e32 v149, v149
	v_exp_f32_e32 v154, v154
	v_exp_f32_e32 v155, v155
	v_exp_f32_e32 v146, v146
	v_add_f32_e32 v149, 1.0, v149
	v_add_f32_e32 v154, 1.0, v154
	v_add_f32_e32 v155, 1.0, v155
	v_add_f32_e32 v146, 1.0, v146
	v_rcp_f32_e32 v149, v149
	v_rcp_f32_e32 v154, v154
	v_rcp_f32_e32 v155, v155
	v_rcp_f32_e32 v157, v146
	v_lshlrev_b64 v[146:147], 12, v[142:143]
	v_lshl_add_u64 v[146:147], s[16:17], 0, v[146:147]
	v_pk_mul_f32 v[128:129], v[128:129], v[154:155]
	v_pk_mul_f32 v[124:125], v[124:125], v[156:157]
	v_pk_mul_f32 v[122:123], v[122:123], v[148:149]
	v_lshl_add_u64 v[146:147], v[140:141], 2, v[146:147]
	s_cbranch_scc1 .LBB0_118
	global_load_dwordx4 v[154:157], v[146:147], off
	global_load_dwordx4 v[158:161], v[146:147], off offset:16
	s_waitcnt vmcnt(0)
	v_pk_add_f32 v[128:129], v[128:129], v[156:157]
	v_pk_add_f32 v[126:127], v[126:127], v[154:155]
	v_pk_add_f32 v[124:125], v[124:125], v[160:161]
	v_pk_add_f32 v[122:123], v[122:123], v[158:159]

; __device__ __forceinline__ float sigm(float x) { return rcpf_(1.f + __expf(-x)); }
; __device__ __forceinline__ void unpack8(u32x4 w, float* e) { e[0] = lo_bf(w.x); e[1] = hi_bf(w.x); e[2] = lo_bf(w.y); e[3] = hi_bf(w.y); e[4] = lo_bf(w.z); e[5] = hi_bf(w.z); e[6] = lo_bf(w.w); e[7] = hi_bf(w.w); }
;     __device__ __forceinline__ void operator()(const f32x4 (&acc)[2][2][4][2], const Unit& u, int wr, int wc, int fr, int fq) const {
;     ...
;                 const int row = row0 + ai * 128 + m * 16;
; #pragma unroll
;                 for (int bj = 0; bj < 2; ++bj) {
;                     const int col = colt + bj * 128;
;                     const u32x4 gw = *(const u32x4*)(P + (size_t)row * NIN + C_GM + u.z * 1024 + col);
;                     float gt[8]; unpack8(gw, gt);
;                     f32x4 v0 = acc[ai][bj][m][0], v1 = acc[ai][bj][m][1];
; #pragma unroll
;                     for (int j = 0; j < 4; ++j) { v0[j] *= sigm(gt[j]); v1[j] *= sigm(gt[4 + j]); }
;                     float* tp = tmp + (size_t)row * 1024 + col;
;                     if (u.z > 0) { v0 += *(const f32x4*)tp; v1 += *(const f32x4*)(tp + 4); }
;                     if (u.z < 2) { *(f32x4*)tp = v0; *(f32x4*)(tp + 4) = v1; }
.LBB0_122:
	s_mov_b64 s[6:7], 0x4000
	s_nop 0
	v_lshl_add_u64 v[122:123], v[144:145], 0, s[6:7]
	v_mov_b32_e32 v122, v196
	v_mov_b32_e32 v123, v197
	v_mov_b32_e32 v124, v198
	v_mov_b32_e32 v125, v199
	v_cndmask_b32_e64 v126, 0, 1, s[8:9]
	v_cmp_ne_u32_e64 s[6:7], 1, v126
	s_andn2_b64 vcc, exec, s[8:9]
	v_lshlrev_b32_e32 v126, 16, v122
	v_and_b32_e32 v122, 0xffff0000, v122
	v_lshlrev_b32_e32 v127, 16, v123
	v_and_b32_e32 v123, 0xffff0000, v123
	v_lshlrev_b32_e32 v128, 16, v124
	v_and_b32_e32 v124, 0xffff0000, v124
	v_lshlrev_b32_e32 v129, 16, v125
	v_and_b32_e32 v125, 0xffff0000, v125
	v_mul_f32_e32 v126, 0xbfb8aa3b, v126
	v_mul_f32_e32 v128, 0xbfb8aa3b, v128
	v_mul_f32_e32 v122, 0xbfb8aa3b, v122
	v_mul_f32_e32 v124, 0xbfb8aa3b, v124
	v_mul_f32_e32 v127, 0xbfb8aa3b, v127
	v_mul_f32_e32 v129, 0xbfb8aa3b, v129
	v_mul_f32_e32 v123, 0xbfb8aa3b, v123
	v_mul_f32_e32 v125, 0xbfb8aa3b, v125
	v_exp_f32_e32 v126, v126
	v_exp_f32_e32 v128, v128
	v_exp_f32_e32 v122, v122
	v_exp_f32_e32 v124, v124
	v_exp_f32_e32 v127, v127
	v_exp_f32_e32 v129, v129
	v_exp_f32_e32 v123, v123
	v_exp_f32_e32 v125, v125
	v_add_f32_e32 v126, 1.0, v126
	v_add_f32_e32 v128, 1.0, v128
	v_add_f32_e32 v143, 1.0, v122
	v_add_f32_e32 v144, 1.0, v124
	v_add_f32_e32 v127, 1.0, v127
	v_add_f32_e32 v129, 1.0, v129
	v_add_f32_e32 v145, 1.0, v123
	v_add_f32_e32 v125, 1.0, v125
	v_rcp_f32_e32 v122, v126
	v_rcp_f32_e32 v124, v128
	v_rcp_f32_e32 v123, v143
	v_rcp_f32_e32 v126, v127
	v_rcp_f32_e32 v127, v145
	v_rcp_f32_e32 v128, v129
	v_rcp_f32_e32 v129, v125
	v_rcp_f32_e32 v125, v144
	v_pk_mul_f32 v[120:121], v[120:121], v[126:127]
	v_pk_mul_f32 v[118:119], v[118:119], v[122:123]
	v_pk_mul_f32 v[116:117], v[116:117], v[128:129]
	v_pk_mul_f32 v[114:115], v[114:115], v[124:125]
	s_cbranch_vccnz .LBB0_124
	global_load_dwordx4 v[122:125], v[146:147], off offset:512
	global_load_dwordx4 v[126:129], v[146:147], off offset:528
	s_waitcnt vmcnt(0)
	v_pk_add_f32 v[120:121], v[120:121], v[124:125]
	v_pk_add_f32 v[118:119], v[118:119], v[122:123]
	v_pk_add_f32 v[116:117], v[116:117], v[128:129]
	v_pk_add_f32 v[114:115], v[114:115], v[126:127]

; __device__ __forceinline__ float sigm(float x) { return rcpf_(1.f + __expf(-x)); }
; __device__ __forceinline__ void unpack8(u32x4 w, float* e) { e[0] = lo_bf(w.x); e[1] = hi_bf(w.x); e[2] = lo_bf(w.y); e[3] = hi_bf(w.y); e[4] = lo_bf(w.z); e[5] = hi_bf(w.z); e[6] = lo_bf(w.w); e[7] = hi_bf(w.w); }
;     __device__ __forceinline__ void operator()(const f32x4 (&acc)[2][2][4][2], const Unit& u, int wr, int wc, int fr, int fq) const {
;     ...
;                 const int row = row0 + ai * 128 + m * 16;
; #pragma unroll
;                 for (int bj = 0; bj < 2; ++bj) {
;                     const int col = colt + bj * 128;
;                     const u32x4 gw = *(const u32x4*)(P + (size_t)row * NIN + C_GM + u.z * 1024 + col);
;                     float gt[8]; unpack8(gw, gt);
;                     f32x4 v0 = acc[ai][bj][m][0], v1 = acc[ai][bj][m][1];
; #pragma unroll
;                     for (int j = 0; j < 4; ++j) { v0[j] *= sigm(gt[j]); v1[j] *= sigm(gt[4 + j]); }
;                     float* tp = tmp + (size_t)row * 1024 + col;
;                     if (u.z > 0) { v0 += *(const f32x4*)tp; v1 += *(const f32x4*)(tp + 4); }
;                     if (u.z < 2) { *(f32x4*)tp = v0; *(f32x4*)(tp + 4) = v1; }
.LBB0_128:
	s_nop 1
	v_or_b32_e32 v116, 16, v142
	v_mov_b64_e32 v[114:115], s[12:13]
	v_mad_i64_i32 v[114:115], s[44:45], v116, s43, v[114:115]
	v_lshl_add_u64 v[114:115], s[38:39], 1, v[114:115]
	v_lshl_add_u64 v[114:115], v[140:141], 1, v[114:115]
	v_add_co_u32_e32 v118, vcc, 0x4000, v114
	v_ashrrev_i32_e32 v117, 31, v116
	s_nop 0
	v_addc_co_u32_e32 v119, vcc, 0, v115, vcc
	v_mov_b32_e32 v118, v162
	v_mov_b32_e32 v119, v163
	v_mov_b32_e32 v120, v164
	v_mov_b32_e32 v121, v165
	s_and_b64 vcc, exec, s[6:7]
	v_lshlrev_b32_e32 v124, 16, v119
	v_and_b32_e32 v125, 0xffff0000, v119
	v_lshlrev_b32_e32 v119, 16, v120
	v_mul_f32_e32 v119, 0xbfb8aa3b, v119
	v_exp_f32_e32 v119, v119
	v_lshlrev_b32_e32 v122, 16, v118
	v_and_b32_e32 v123, 0xffff0000, v118
	v_and_b32_e32 v126, 0xffff0000, v120
	v_add_f32_e32 v119, 1.0, v119
	v_mul_f32_e32 v118, 0xbfb8aa3b, v122
	v_rcp_f32_e32 v120, v119
	v_mul_f32_e32 v119, 0xbfb8aa3b, v123
	v_exp_f32_e32 v118, v118
	v_exp_f32_e32 v119, v119
	v_lshlrev_b32_e32 v127, 16, v121
	v_mul_f32_e32 v123, 0xbfb8aa3b, v127
	v_add_f32_e32 v118, 1.0, v118
	v_add_f32_e32 v119, 1.0, v119
	v_exp_f32_e32 v123, v123
	v_rcp_f32_e32 v118, v118
	v_rcp_f32_e32 v119, v119
	v_and_b32_e32 v128, 0xffff0000, v121
	v_add_f32_e32 v123, 1.0, v123
	v_mul_f32_e32 v121, 0xbfb8aa3b, v126
	v_mul_f32_e32 v122, 0xbfb8aa3b, v124
	v_rcp_f32_e32 v124, v123
	v_mul_f32_e32 v123, 0xbfb8aa3b, v125
	v_pk_mul_f32 v[110:111], v[110:111], v[118:119]
	v_mul_f32_e32 v118, 0xbfb8aa3b, v128
	v_exp_f32_e32 v121, v121
	v_exp_f32_e32 v122, v122
	v_exp_f32_e32 v123, v123
	v_exp_f32_e32 v118, v118
	v_add_f32_e32 v121, 1.0, v121
	v_add_f32_e32 v122, 1.0, v122
	v_add_f32_e32 v123, 1.0, v123
	v_add_f32_e32 v118, 1.0, v118
	v_rcp_f32_e32 v121, v121
	v_rcp_f32_e32 v122, v122
	v_rcp_f32_e32 v123, v123
	v_rcp_f32_e32 v125, v118
	v_lshlrev_b64 v[118:119], 12, v[116:117]
	v_lshl_add_u64 v[118:119], s[16:17], 0, v[118:119]
	v_pk_mul_f32 v[112:113], v[112:113], v[122:123]
	v_pk_mul_f32 v[108:109], v[108:109], v[124:125]
	v_pk_mul_f32 v[106:107], v[106:107], v[120:121]
	v_lshl_add_u64 v[118:119], v[140:141], 2, v[118:119]
	s_cbranch_vccnz .LBB0_130
	global_load_dwordx4 v[120:123], v[118:119], off
	global_load_dwordx4 v[124:127], v[118:119], off offset:16
	s_waitcnt vmcnt(0)
	v_pk_add_f32 v[112:113], v[112:113], v[122:123]
	v_pk_add_f32 v[110:111], v[110:111], v[120:121]
	v_pk_add_f32 v[108:109], v[108:109], v[126:127]
	v_pk_add_f32 v[106:107], v[106:107], v[124:125]

; __device__ __forceinline__ float sigm(float x) { return rcpf_(1.f + __expf(-x)); }
; __device__ __forceinline__ void unpack8(u32x4 w, float* e) { e[0] = lo_bf(w.x); e[1] = hi_bf(w.x); e[2] = lo_bf(w.y); e[3] = hi_bf(w.y); e[4] = lo_bf(w.z); e[5] = hi_bf(w.z); e[6] = lo_bf(w.w); e[7] = hi_bf(w.w); }
;     __device__ __forceinline__ void operator()(const f32x4 (&acc)[2][2][4][2], const Unit& u, int wr, int wc, int fr, int fq) const {
;     ...
;                 const int row = row0 + ai * 128 + m * 16;
; #pragma unroll
;                 for (int bj = 0; bj < 2; ++bj) {
;                     const int col = colt + bj * 128;
;                     const u32x4 gw = *(const u32x4*)(P + (size_t)row * NIN + C_GM + u.z * 1024 + col);
;                     float gt[8]; unpack8(gw, gt);
;                     f32x4 v0 = acc[ai][bj][m][0], v1 = acc[ai][bj][m][1];
; #pragma unroll
;                     for (int j = 0; j < 4; ++j) { v0[j] *= sigm(gt[j]); v1[j] *= sigm(gt[4 + j]); }
;                     float* tp = tmp + (size_t)row * 1024 + col;
;                     if (u.z > 0) { v0 += *(const f32x4*)tp; v1 += *(const f32x4*)(tp + 4); }
;                     if (u.z < 2) { *(f32x4*)tp = v0; *(f32x4*)(tp + 4) = v1; }
.LBB0_134:
	s_mov_b64 s[44:45], 0x4000
	s_nop 0
	v_lshl_add_u64 v[106:107], v[114:115], 0, s[44:45]
	v_mov_b32_e32 v106, v200
	v_mov_b32_e32 v107, v201
	v_mov_b32_e32 v108, v202
	v_mov_b32_e32 v109, v203
	s_and_b64 vcc, exec, s[6:7]
	v_lshlrev_b32_e32 v110, 16, v106
	v_and_b32_e32 v106, 0xffff0000, v106
	v_lshlrev_b32_e32 v111, 16, v107
	v_and_b32_e32 v107, 0xffff0000, v107
	v_lshlrev_b32_e32 v112, 16, v108
	v_and_b32_e32 v108, 0xffff0000, v108
	v_lshlrev_b32_e32 v113, 16, v109
	v_and_b32_e32 v109, 0xffff0000, v109
	v_mul_f32_e32 v110, 0xbfb8aa3b, v110
	v_mul_f32_e32 v112, 0xbfb8aa3b, v112
	v_mul_f32_e32 v106, 0xbfb8aa3b, v106
	v_mul_f32_e32 v108, 0xbfb8aa3b, v108
	v_mul_f32_e32 v111, 0xbfb8aa3b, v111
	v_mul_f32_e32 v113, 0xbfb8aa3b, v113
	v_mul_f32_e32 v107, 0xbfb8aa3b, v107
	v_mul_f32_e32 v109, 0xbfb8aa3b, v109
	v_exp_f32_e32 v110, v110
	v_exp_f32_e32 v112, v112
	v_exp_f32_e32 v106, v106
	v_exp_f32_e32 v108, v108
	v_exp_f32_e32 v111, v111
	v_exp_f32_e32 v113, v113
	v_exp_f32_e32 v107, v107
	v_exp_f32_e32 v109, v109
	v_add_f32_e32 v110, 1.0, v110
	v_add_f32_e32 v112, 1.0, v112
	v_add_f32_e32 v114, 1.0, v106
	v_add_f32_e32 v115, 1.0, v108
	v_add_f32_e32 v111, 1.0, v111
	v_add_f32_e32 v113, 1.0, v113
	v_add_f32_e32 v120, 1.0, v107
	v_add_f32_e32 v109, 1.0, v109
	v_rcp_f32_e32 v106, v110
	v_rcp_f32_e32 v108, v112
	v_rcp_f32_e32 v107, v114
	v_rcp_f32_e32 v110, v111
	v_rcp_f32_e32 v111, v120
	v_rcp_f32_e32 v112, v113
	v_rcp_f32_e32 v113, v109
	v_rcp_f32_e32 v109, v115
	v_pk_mul_f32 v[104:105], v[104:105], v[110:111]
	v_pk_mul_f32 v[102:103], v[102:103], v[106:107]
	v_pk_mul_f32 v[100:101], v[100:101], v[112:113]
	v_pk_mul_f32 v[98:99], v[98:99], v[108:109]
	s_cbranch_vccnz .LBB0_136
	global_load_dwordx4 v[106:109], v[118:119], off offset:512
	global_load_dwordx4 v[110:113], v[118:119], off offset:528
	s_waitcnt vmcnt(0)
	v_pk_add_f32 v[104:105], v[104:105], v[108:109]
	v_pk_add_f32 v[102:103], v[102:103], v[106:107]
	v_pk_add_f32 v[100:101], v[100:101], v[112:113]
	v_pk_add_f32 v[98:99], v[98:99], v[110:111]

; __device__ __forceinline__ float sigm(float x) { return rcpf_(1.f + __expf(-x)); }
; __device__ __forceinline__ void unpack8(u32x4 w, float* e) { e[0] = lo_bf(w.x); e[1] = hi_bf(w.x); e[2] = lo_bf(w.y); e[3] = hi_bf(w.y); e[4] = lo_bf(w.z); e[5] = hi_bf(w.z); e[6] = lo_bf(w.w); e[7] = hi_bf(w.w); }
;     __device__ __forceinline__ void operator()(const f32x4 (&acc)[2][2][4][2], const Unit& u, int wr, int wc, int fr, int fq) const {
;     ...
;                 const int row = row0 + ai * 128 + m * 16;
; #pragma unroll
;                 for (int bj = 0; bj < 2; ++bj) {
;                     const int col = colt + bj * 128;
;                     const u32x4 gw = *(const u32x4*)(P + (size_t)row * NIN + C_GM + u.z * 1024 + col);
;                     float gt[8]; unpack8(gw, gt);
;                     f32x4 v0 = acc[ai][bj][m][0], v1 = acc[ai][bj][m][1];
; #pragma unroll
;                     for (int j = 0; j < 4; ++j) { v0[j] *= sigm(gt[j]); v1[j] *= sigm(gt[4 + j]); }
;                     float* tp = tmp + (size_t)row * 1024 + col;
;                     if (u.z > 0) { v0 += *(const f32x4*)tp; v1 += *(const f32x4*)(tp + 4); }
;                     if (u.z < 2) { *(f32x4*)tp = v0; *(f32x4*)(tp + 4) = v1; }
.LBB0_140:
	s_nop 1
	v_or_b32_e32 v100, 32, v142
	v_mov_b64_e32 v[98:99], s[12:13]
	v_mad_i64_i32 v[98:99], s[44:45], v100, s43, v[98:99]
	v_lshl_add_u64 v[98:99], s[38:39], 1, v[98:99]
	v_lshl_add_u64 v[98:99], v[140:141], 1, v[98:99]
	v_add_co_u32_e32 v102, vcc, 0x4000, v98
	v_ashrrev_i32_e32 v101, 31, v100
	s_nop 0
	v_addc_co_u32_e32 v103, vcc, 0, v99, vcc
	v_mov_b32_e32 v102, v166
	v_mov_b32_e32 v103, v167
	v_mov_b32_e32 v104, v168
	v_mov_b32_e32 v105, v169
	s_and_b64 vcc, exec, s[6:7]
	v_lshlrev_b32_e32 v108, 16, v103
	v_and_b32_e32 v109, 0xffff0000, v103
	v_lshlrev_b32_e32 v103, 16, v104
	v_mul_f32_e32 v103, 0xbfb8aa3b, v103
	v_exp_f32_e32 v103, v103
	v_lshlrev_b32_e32 v106, 16, v102
	v_and_b32_e32 v107, 0xffff0000, v102
	v_and_b32_e32 v110, 0xffff0000, v104
	v_add_f32_e32 v103, 1.0, v103
	v_mul_f32_e32 v102, 0xbfb8aa3b, v106
	v_rcp_f32_e32 v104, v103
	v_mul_f32_e32 v103, 0xbfb8aa3b, v107
	v_exp_f32_e32 v102, v102
	v_exp_f32_e32 v103, v103
	v_lshlrev_b32_e32 v111, 16, v105
	v_mul_f32_e32 v107, 0xbfb8aa3b, v111
	v_add_f32_e32 v102, 1.0, v102
	v_add_f32_e32 v103, 1.0, v103
	v_exp_f32_e32 v107, v107
	v_rcp_f32_e32 v102, v102
	v_rcp_f32_e32 v103, v103
	v_and_b32_e32 v112, 0xffff0000, v105
	v_add_f32_e32 v107, 1.0, v107
	v_mul_f32_e32 v105, 0xbfb8aa3b, v110
	v_mul_f32_e32 v106, 0xbfb8aa3b, v108
	v_rcp_f32_e32 v108, v107
	v_mul_f32_e32 v107, 0xbfb8aa3b, v109
	v_pk_mul_f32 v[94:95], v[94:95], v[102:103]
	v_mul_f32_e32 v102, 0xbfb8aa3b, v112
	v_exp_f32_e32 v105, v105
	v_exp_f32_e32 v106, v106
	v_exp_f32_e32 v107, v107
	v_exp_f32_e32 v102, v102
	v_add_f32_e32 v105, 1.0, v105
	v_add_f32_e32 v106, 1.0, v106
	v_add_f32_e32 v107, 1.0, v107
	v_add_f32_e32 v102, 1.0, v102
	v_rcp_f32_e32 v105, v105
	v_rcp_f32_e32 v106, v106
	v_rcp_f32_e32 v107, v107
	v_rcp_f32_e32 v109, v102
	v_lshlrev_b64 v[102:103], 12, v[100:101]
	v_lshl_add_u64 v[102:103], s[16:17], 0, v[102:103]
	v_pk_mul_f32 v[96:97], v[96:97], v[106:107]
	v_pk_mul_f32 v[92:93], v[92:93], v[108:109]
	v_pk_mul_f32 v[90:91], v[90:91], v[104:105]
	v_lshl_add_u64 v[102:103], v[140:141], 2, v[102:103]
	s_cbranch_vccnz .LBB0_142
	global_load_dwordx4 v[104:107], v[102:103], off
	global_load_dwordx4 v[108:111], v[102:103], off offset:16
	s_waitcnt vmcnt(0)
	v_pk_add_f32 v[96:97], v[96:97], v[106:107]
	v_pk_add_f32 v[94:95], v[94:95], v[104:105]
	v_pk_add_f32 v[92:93], v[92:93], v[110:111]
	v_pk_add_f32 v[90:91], v[90:91], v[108:109]

; __device__ __forceinline__ float sigm(float x) { return rcpf_(1.f + __expf(-x)); }
; __device__ __forceinline__ void unpack8(u32x4 w, float* e) { e[0] = lo_bf(w.x); e[1] = hi_bf(w.x); e[2] = lo_bf(w.y); e[3] = hi_bf(w.y); e[4] = lo_bf(w.z); e[5] = hi_bf(w.z); e[6] = lo_bf(w.w); e[7] = hi_bf(w.w); }
;     __device__ __forceinline__ void operator()(const f32x4 (&acc)[2][2][4][2], const Unit& u, int wr, int wc, int fr, int fq) const {
;     ...
;                 const int row = row0 + ai * 128 + m * 16;
; #pragma unroll
;                 for (int bj = 0; bj < 2; ++bj) {
;                     const int col = colt + bj * 128;
;                     const u32x4 gw = *(const u32x4*)(P + (size_t)row * NIN + C_GM + u.z * 1024 + col);
;                     float gt[8]; unpack8(gw, gt);
;                     f32x4 v0 = acc[ai][bj][m][0], v1 = acc[ai][bj][m][1];
; #pragma unroll
;                     for (int j = 0; j < 4; ++j) { v0[j] *= sigm(gt[j]); v1[j] *= sigm(gt[4 + j]); }
;                     float* tp = tmp + (size_t)row * 1024 + col;
;                     if (u.z > 0) { v0 += *(const f32x4*)tp; v1 += *(const f32x4*)(tp + 4); }
;                     if (u.z < 2) { *(f32x4*)tp = v0; *(f32x4*)(tp + 4) = v1; }
.LBB0_146:
	s_mov_b64 s[44:45], 0x4000
	s_nop 0
	v_lshl_add_u64 v[90:91], v[98:99], 0, s[44:45]
	v_mov_b32_e32 v90, v204
	v_mov_b32_e32 v91, v205
	v_mov_b32_e32 v92, v206
	v_mov_b32_e32 v93, v207
	s_and_b64 vcc, exec, s[6:7]
	v_lshlrev_b32_e32 v94, 16, v90
	v_and_b32_e32 v90, 0xffff0000, v90
	v_lshlrev_b32_e32 v95, 16, v91
	v_and_b32_e32 v91, 0xffff0000, v91
	v_lshlrev_b32_e32 v96, 16, v92
	v_and_b32_e32 v92, 0xffff0000, v92
	v_lshlrev_b32_e32 v97, 16, v93
	v_and_b32_e32 v93, 0xffff0000, v93
	v_mul_f32_e32 v94, 0xbfb8aa3b, v94
	v_mul_f32_e32 v96, 0xbfb8aa3b, v96
	v_mul_f32_e32 v90, 0xbfb8aa3b, v90
	v_mul_f32_e32 v92, 0xbfb8aa3b, v92
	v_mul_f32_e32 v95, 0xbfb8aa3b, v95
	v_mul_f32_e32 v97, 0xbfb8aa3b, v97
	v_mul_f32_e32 v91, 0xbfb8aa3b, v91
	v_mul_f32_e32 v93, 0xbfb8aa3b, v93
	v_exp_f32_e32 v94, v94
	v_exp_f32_e32 v96, v96
	v_exp_f32_e32 v90, v90
	v_exp_f32_e32 v92, v92
	v_exp_f32_e32 v95, v95
	v_exp_f32_e32 v97, v97
	v_exp_f32_e32 v91, v91
	v_exp_f32_e32 v93, v93
	v_add_f32_e32 v94, 1.0, v94
	v_add_f32_e32 v96, 1.0, v96
	v_add_f32_e32 v98, 1.0, v90
	v_add_f32_e32 v99, 1.0, v92
	v_add_f32_e32 v95, 1.0, v95
	v_add_f32_e32 v97, 1.0, v97
	v_add_f32_e32 v104, 1.0, v91
	v_add_f32_e32 v93, 1.0, v93
	v_rcp_f32_e32 v90, v94
	v_rcp_f32_e32 v92, v96
	v_rcp_f32_e32 v91, v98
	v_rcp_f32_e32 v94, v95
	v_rcp_f32_e32 v95, v104
	v_rcp_f32_e32 v96, v97
	v_rcp_f32_e32 v97, v93
	v_rcp_f32_e32 v93, v99
	v_pk_mul_f32 v[88:89], v[88:89], v[94:95]
	v_pk_mul_f32 v[86:87], v[86:87], v[90:91]
	v_pk_mul_f32 v[84:85], v[84:85], v[96:97]
	v_pk_mul_f32 v[82:83], v[82:83], v[92:93]
	s_cbranch_vccnz .LBB0_148
	global_load_dwordx4 v[90:93], v[102:103], off offset:512
	global_load_dwordx4 v[94:97], v[102:103], off offset:528
	s_waitcnt vmcnt(0)
	v_pk_add_f32 v[88:89], v[88:89], v[92:93]
	v_pk_add_f32 v[86:87], v[86:87], v[90:91]
	v_pk_add_f32 v[84:85], v[84:85], v[96:97]
	v_pk_add_f32 v[82:83], v[82:83], v[94:95]

; __device__ __forceinline__ float sigm(float x) { return rcpf_(1.f + __expf(-x)); }
; __device__ __forceinline__ void unpack8(u32x4 w, float* e) { e[0] = lo_bf(w.x); e[1] = hi_bf(w.x); e[2] = lo_bf(w.y); e[3] = hi_bf(w.y); e[4] = lo_bf(w.z); e[5] = hi_bf(w.z); e[6] = lo_bf(w.w); e[7] = hi_bf(w.w); }
;     __device__ __forceinline__ void operator()(const f32x4 (&acc)[2][2][4][2], const Unit& u, int wr, int wc, int fr, int fq) const {
;     ...
;                 const int row = row0 + ai * 128 + m * 16;
; #pragma unroll
;                 for (int bj = 0; bj < 2; ++bj) {
;                     const int col = colt + bj * 128;
;                     const u32x4 gw = *(const u32x4*)(P + (size_t)row * NIN + C_GM + u.z * 1024 + col);
;                     float gt[8]; unpack8(gw, gt);
;                     f32x4 v0 = acc[ai][bj][m][0], v1 = acc[ai][bj][m][1];
; #pragma unroll
;                     for (int j = 0; j < 4; ++j) { v0[j] *= sigm(gt[j]); v1[j] *= sigm(gt[4 + j]); }
;                     float* tp = tmp + (size_t)row * 1024 + col;
;                     if (u.z > 0) { v0 += *(const f32x4*)tp; v1 += *(const f32x4*)(tp + 4); }
;                     if (u.z < 2) { *(f32x4*)tp = v0; *(f32x4*)(tp + 4) = v1; }
.LBB0_152:
	s_nop 1
	v_or_b32_e32 v84, 48, v142
	v_mov_b64_e32 v[82:83], s[12:13]
	v_mad_i64_i32 v[82:83], s[44:45], v84, s43, v[82:83]
	v_lshl_add_u64 v[82:83], s[38:39], 1, v[82:83]
	v_lshl_add_u64 v[82:83], v[140:141], 1, v[82:83]
	v_add_co_u32_e32 v86, vcc, 0x4000, v82
	v_ashrrev_i32_e32 v85, 31, v84
	s_nop 0
	v_addc_co_u32_e32 v87, vcc, 0, v83, vcc
	v_mov_b32_e32 v86, v170
	v_mov_b32_e32 v87, v171
	v_mov_b32_e32 v88, v172
	v_mov_b32_e32 v89, v173
	s_and_b64 vcc, exec, s[6:7]
	v_lshlrev_b32_e32 v92, 16, v87
	v_and_b32_e32 v93, 0xffff0000, v87
	v_lshlrev_b32_e32 v87, 16, v88
	v_mul_f32_e32 v87, 0xbfb8aa3b, v87
	v_exp_f32_e32 v87, v87
	v_lshlrev_b32_e32 v90, 16, v86
	v_and_b32_e32 v91, 0xffff0000, v86
	v_and_b32_e32 v94, 0xffff0000, v88
	v_add_f32_e32 v87, 1.0, v87
	v_mul_f32_e32 v86, 0xbfb8aa3b, v90
	v_rcp_f32_e32 v88, v87
	v_mul_f32_e32 v87, 0xbfb8aa3b, v91
	v_exp_f32_e32 v86, v86
	v_exp_f32_e32 v87, v87
	v_lshlrev_b32_e32 v95, 16, v89
	v_mul_f32_e32 v91, 0xbfb8aa3b, v95
	v_add_f32_e32 v86, 1.0, v86
	v_add_f32_e32 v87, 1.0, v87
	v_exp_f32_e32 v91, v91
	v_rcp_f32_e32 v86, v86
	v_rcp_f32_e32 v87, v87
	v_and_b32_e32 v96, 0xffff0000, v89
	v_add_f32_e32 v91, 1.0, v91
	v_mul_f32_e32 v89, 0xbfb8aa3b, v94
	v_mul_f32_e32 v90, 0xbfb8aa3b, v92
	v_rcp_f32_e32 v92, v91
	v_mul_f32_e32 v91, 0xbfb8aa3b, v93
	v_pk_mul_f32 v[78:79], v[78:79], v[86:87]
	v_mul_f32_e32 v86, 0xbfb8aa3b, v96
	v_exp_f32_e32 v89, v89
	v_exp_f32_e32 v90, v90
	v_exp_f32_e32 v91, v91
	v_exp_f32_e32 v86, v86
	v_add_f32_e32 v89, 1.0, v89
	v_add_f32_e32 v90, 1.0, v90
	v_add_f32_e32 v91, 1.0, v91
	v_add_f32_e32 v86, 1.0, v86
	v_rcp_f32_e32 v89, v89
	v_rcp_f32_e32 v90, v90
	v_rcp_f32_e32 v91, v91
	v_rcp_f32_e32 v93, v86
	v_lshlrev_b64 v[86:87], 12, v[84:85]
	v_lshl_add_u64 v[86:87], s[16:17], 0, v[86:87]
	v_pk_mul_f32 v[80:81], v[80:81], v[90:91]
	v_pk_mul_f32 v[76:77], v[76:77], v[92:93]
	v_pk_mul_f32 v[74:75], v[74:75], v[88:89]
	v_lshl_add_u64 v[86:87], v[140:141], 2, v[86:87]
	s_cbranch_vccnz .LBB0_154
	global_load_dwordx4 v[88:91], v[86:87], off
	global_load_dwordx4 v[92:95], v[86:87], off offset:16
	s_waitcnt vmcnt(0)
	v_pk_add_f32 v[80:81], v[80:81], v[90:91]
	v_pk_add_f32 v[78:79], v[78:79], v[88:89]
	v_pk_add_f32 v[76:77], v[76:77], v[94:95]
	v_pk_add_f32 v[74:75], v[74:75], v[92:93]

; __device__ __forceinline__ float sigm(float x) { return rcpf_(1.f + __expf(-x)); }
; __device__ __forceinline__ void unpack8(u32x4 w, float* e) { e[0] = lo_bf(w.x); e[1] = hi_bf(w.x); e[2] = lo_bf(w.y); e[3] = hi_bf(w.y); e[4] = lo_bf(w.z); e[5] = hi_bf(w.z); e[6] = lo_bf(w.w); e[7] = hi_bf(w.w); }
;     __device__ __forceinline__ void operator()(const f32x4 (&acc)[2][2][4][2], const Unit& u, int wr, int wc, int fr, int fq) const {
;     ...
;                 const int row = row0 + ai * 128 + m * 16;
; #pragma unroll
;                 for (int bj = 0; bj < 2; ++bj) {
;                     const int col = colt + bj * 128;
;                     const u32x4 gw = *(const u32x4*)(P + (size_t)row * NIN + C_GM + u.z * 1024 + col);
;                     float gt[8]; unpack8(gw, gt);
;                     f32x4 v0 = acc[ai][bj][m][0], v1 = acc[ai][bj][m][1];
; #pragma unroll
;                     for (int j = 0; j < 4; ++j) { v0[j] *= sigm(gt[j]); v1[j] *= sigm(gt[4 + j]); }
;                     float* tp = tmp + (size_t)row * 1024 + col;
;                     if (u.z > 0) { v0 += *(const f32x4*)tp; v1 += *(const f32x4*)(tp + 4); }
;                     if (u.z < 2) { *(f32x4*)tp = v0; *(f32x4*)(tp + 4) = v1; }
.LBB0_158:
	s_mov_b64 s[44:45], 0x4000
	s_nop 0
	v_lshl_add_u64 v[74:75], v[82:83], 0, s[44:45]
	v_mov_b32_e32 v74, v208
	v_mov_b32_e32 v75, v209
	v_mov_b32_e32 v76, v210
	v_mov_b32_e32 v77, v211
	s_and_b64 vcc, exec, s[6:7]
	v_lshlrev_b32_e32 v78, 16, v74
	v_and_b32_e32 v74, 0xffff0000, v74
	v_lshlrev_b32_e32 v79, 16, v75
	v_and_b32_e32 v75, 0xffff0000, v75
	v_lshlrev_b32_e32 v80, 16, v76
	v_and_b32_e32 v76, 0xffff0000, v76
	v_lshlrev_b32_e32 v81, 16, v77
	v_and_b32_e32 v77, 0xffff0000, v77
	v_mul_f32_e32 v78, 0xbfb8aa3b, v78
	v_mul_f32_e32 v80, 0xbfb8aa3b, v80
	v_mul_f32_e32 v74, 0xbfb8aa3b, v74
	v_mul_f32_e32 v76, 0xbfb8aa3b, v76
	v_mul_f32_e32 v79, 0xbfb8aa3b, v79
	v_mul_f32_e32 v81, 0xbfb8aa3b, v81
	v_mul_f32_e32 v75, 0xbfb8aa3b, v75
	v_mul_f32_e32 v77, 0xbfb8aa3b, v77
	v_exp_f32_e32 v78, v78
	v_exp_f32_e32 v80, v80
	v_exp_f32_e32 v74, v74
	v_exp_f32_e32 v76, v76
	v_exp_f32_e32 v79, v79
	v_exp_f32_e32 v81, v81
	v_exp_f32_e32 v75, v75
	v_exp_f32_e32 v77, v77
	v_add_f32_e32 v78, 1.0, v78
	v_add_f32_e32 v80, 1.0, v80
	v_add_f32_e32 v82, 1.0, v74
	v_add_f32_e32 v83, 1.0, v76
	v_add_f32_e32 v79, 1.0, v79
	v_add_f32_e32 v81, 1.0, v81
	v_add_f32_e32 v88, 1.0, v75
	v_add_f32_e32 v77, 1.0, v77
	v_rcp_f32_e32 v74, v78
	v_rcp_f32_e32 v76, v80
	v_rcp_f32_e32 v75, v82
	v_rcp_f32_e32 v78, v79
	v_rcp_f32_e32 v79, v88
	v_rcp_f32_e32 v80, v81
	v_rcp_f32_e32 v81, v77
	v_rcp_f32_e32 v77, v83
	v_pk_mul_f32 v[72:73], v[72:73], v[78:79]
	v_pk_mul_f32 v[70:71], v[70:71], v[74:75]
	v_pk_mul_f32 v[68:69], v[68:69], v[80:81]
	v_pk_mul_f32 v[66:67], v[66:67], v[76:77]
	s_cbranch_vccnz .LBB0_160
	global_load_dwordx4 v[74:77], v[86:87], off offset:512
	global_load_dwordx4 v[78:81], v[86:87], off offset:528
	s_waitcnt vmcnt(0)
	v_pk_add_f32 v[72:73], v[72:73], v[76:77]
	v_pk_add_f32 v[70:71], v[70:71], v[74:75]
	v_pk_add_f32 v[68:69], v[68:69], v[80:81]
	v_pk_add_f32 v[66:67], v[66:67], v[78:79]

; __device__ __forceinline__ float sigm(float x) { return rcpf_(1.f + __expf(-x)); }
; __device__ __forceinline__ void unpack8(u32x4 w, float* e) { e[0] = lo_bf(w.x); e[1] = hi_bf(w.x); e[2] = lo_bf(w.y); e[3] = hi_bf(w.y); e[4] = lo_bf(w.z); e[5] = hi_bf(w.z); e[6] = lo_bf(w.w); e[7] = hi_bf(w.w); }
;     __device__ __forceinline__ void operator()(const f32x4 (&acc)[2][2][4][2], const Unit& u, int wr, int wc, int fr, int fq) const {
;     ...
;                 const int row = row0 + ai * 128 + m * 16;
; #pragma unroll
;                 for (int bj = 0; bj < 2; ++bj) {
;                     const int col = colt + bj * 128;
;                     const u32x4 gw = *(const u32x4*)(P + (size_t)row * NIN + C_GM + u.z * 1024 + col);
;                     float gt[8]; unpack8(gw, gt);
;                     f32x4 v0 = acc[ai][bj][m][0], v1 = acc[ai][bj][m][1];
; #pragma unroll
;                     for (int j = 0; j < 4; ++j) { v0[j] *= sigm(gt[j]); v1[j] *= sigm(gt[4 + j]); }
;                     float* tp = tmp + (size_t)row * 1024 + col;
;                     if (u.z > 0) { v0 += *(const f32x4*)tp; v1 += *(const f32x4*)(tp + 4); }
;                     if (u.z < 2) { *(f32x4*)tp = v0; *(f32x4*)(tp + 4) = v1; }
.LBB0_164:
	s_nop 1
	v_add_u32_e32 v68, 0x80, v142
	v_mov_b64_e32 v[66:67], s[12:13]
	v_mad_i64_i32 v[66:67], s[44:45], v68, s43, v[66:67]
	v_lshl_add_u64 v[66:67], s[38:39], 1, v[66:67]
	v_lshl_add_u64 v[66:67], v[140:141], 1, v[66:67]
	v_add_co_u32_e32 v70, vcc, 0x4000, v66
	v_ashrrev_i32_e32 v69, 31, v68
	s_nop 0
	v_addc_co_u32_e32 v71, vcc, 0, v67, vcc
	v_mov_b32_e32 v70, v174
	v_mov_b32_e32 v71, v175
	v_mov_b32_e32 v72, v176
	v_mov_b32_e32 v73, v177
	s_and_b64 vcc, exec, s[6:7]
	v_lshlrev_b32_e32 v76, 16, v71
	v_and_b32_e32 v77, 0xffff0000, v71
	v_lshlrev_b32_e32 v71, 16, v72
	v_mul_f32_e32 v71, 0xbfb8aa3b, v71
	v_exp_f32_e32 v71, v71
	v_lshlrev_b32_e32 v74, 16, v70
	v_and_b32_e32 v75, 0xffff0000, v70
	v_and_b32_e32 v78, 0xffff0000, v72
	v_add_f32_e32 v71, 1.0, v71
	v_mul_f32_e32 v70, 0xbfb8aa3b, v74
	v_rcp_f32_e32 v72, v71
	v_mul_f32_e32 v71, 0xbfb8aa3b, v75
	v_exp_f32_e32 v70, v70
	v_exp_f32_e32 v71, v71
	v_lshlrev_b32_e32 v79, 16, v73
	v_mul_f32_e32 v75, 0xbfb8aa3b, v79
	v_add_f32_e32 v70, 1.0, v70
	v_add_f32_e32 v71, 1.0, v71
	v_exp_f32_e32 v75, v75
	v_rcp_f32_e32 v70, v70
	v_rcp_f32_e32 v71, v71
	v_and_b32_e32 v80, 0xffff0000, v73
	v_add_f32_e32 v75, 1.0, v75
	v_mul_f32_e32 v73, 0xbfb8aa3b, v78
	v_mul_f32_e32 v74, 0xbfb8aa3b, v76
	v_rcp_f32_e32 v76, v75
	v_mul_f32_e32 v75, 0xbfb8aa3b, v77
	v_pk_mul_f32 v[62:63], v[62:63], v[70:71]
	v_mul_f32_e32 v70, 0xbfb8aa3b, v80
	v_exp_f32_e32 v73, v73
	v_exp_f32_e32 v74, v74
	v_exp_f32_e32 v75, v75
	v_exp_f32_e32 v70, v70
	v_add_f32_e32 v73, 1.0, v73
	v_add_f32_e32 v74, 1.0, v74
	v_add_f32_e32 v75, 1.0, v75
	v_add_f32_e32 v70, 1.0, v70
	v_rcp_f32_e32 v73, v73
	v_rcp_f32_e32 v74, v74
	v_rcp_f32_e32 v75, v75
	v_rcp_f32_e32 v77, v70
	v_lshlrev_b64 v[70:71], 12, v[68:69]
	v_lshl_add_u64 v[70:71], s[16:17], 0, v[70:71]
	v_pk_mul_f32 v[64:65], v[64:65], v[74:75]
	v_pk_mul_f32 v[60:61], v[60:61], v[76:77]
	v_pk_mul_f32 v[58:59], v[58:59], v[72:73]
	v_lshl_add_u64 v[70:71], v[140:141], 2, v[70:71]
	s_cbranch_vccnz .LBB0_166
	global_load_dwordx4 v[72:75], v[70:71], off
	global_load_dwordx4 v[76:79], v[70:71], off offset:16
	s_waitcnt vmcnt(0)
	v_pk_add_f32 v[64:65], v[64:65], v[74:75]
	v_pk_add_f32 v[62:63], v[62:63], v[72:73]
	v_pk_add_f32 v[60:61], v[60:61], v[78:79]
	v_pk_add_f32 v[58:59], v[58:59], v[76:77]

; __device__ __forceinline__ float sigm(float x) { return rcpf_(1.f + __expf(-x)); }
; __device__ __forceinline__ void unpack8(u32x4 w, float* e) { e[0] = lo_bf(w.x); e[1] = hi_bf(w.x); e[2] = lo_bf(w.y); e[3] = hi_bf(w.y); e[4] = lo_bf(w.z); e[5] = hi_bf(w.z); e[6] = lo_bf(w.w); e[7] = hi_bf(w.w); }
;     __device__ __forceinline__ void operator()(const f32x4 (&acc)[2][2][4][2], const Unit& u, int wr, int wc, int fr, int fq) const {
;     ...
;                 const int row = row0 + ai * 128 + m * 16;
; #pragma unroll
;                 for (int bj = 0; bj < 2; ++bj) {
;                     const int col = colt + bj * 128;
;                     const u32x4 gw = *(const u32x4*)(P + (size_t)row * NIN + C_GM + u.z * 1024 + col);
;                     float gt[8]; unpack8(gw, gt);
;                     f32x4 v0 = acc[ai][bj][m][0], v1 = acc[ai][bj][m][1];
; #pragma unroll
;                     for (int j = 0; j < 4; ++j) { v0[j] *= sigm(gt[j]); v1[j] *= sigm(gt[4 + j]); }
;                     float* tp = tmp + (size_t)row * 1024 + col;
;                     if (u.z > 0) { v0 += *(const f32x4*)tp; v1 += *(const f32x4*)(tp + 4); }
;                     if (u.z < 2) { *(f32x4*)tp = v0; *(f32x4*)(tp + 4) = v1; }
.LBB0_170:
	s_mov_b64 s[44:45], 0x4000
	s_nop 0
	v_lshl_add_u64 v[58:59], v[66:67], 0, s[44:45]
	v_mov_b32_e32 v58, v212
	v_mov_b32_e32 v59, v213
	v_mov_b32_e32 v60, v214
	v_mov_b32_e32 v61, v215
	s_and_b64 vcc, exec, s[6:7]
	v_lshlrev_b32_e32 v62, 16, v58
	v_and_b32_e32 v58, 0xffff0000, v58
	v_lshlrev_b32_e32 v63, 16, v59
	v_and_b32_e32 v59, 0xffff0000, v59
	v_lshlrev_b32_e32 v64, 16, v60
	v_and_b32_e32 v60, 0xffff0000, v60
	v_lshlrev_b32_e32 v65, 16, v61
	v_and_b32_e32 v61, 0xffff0000, v61
	v_mul_f32_e32 v62, 0xbfb8aa3b, v62
	v_mul_f32_e32 v64, 0xbfb8aa3b, v64
	v_mul_f32_e32 v58, 0xbfb8aa3b, v58
	v_mul_f32_e32 v60, 0xbfb8aa3b, v60
	v_mul_f32_e32 v63, 0xbfb8aa3b, v63
	v_mul_f32_e32 v65, 0xbfb8aa3b, v65
	v_mul_f32_e32 v59, 0xbfb8aa3b, v59
	v_mul_f32_e32 v61, 0xbfb8aa3b, v61
	v_exp_f32_e32 v62, v62
	v_exp_f32_e32 v64, v64
	v_exp_f32_e32 v58, v58
	v_exp_f32_e32 v60, v60
	v_exp_f32_e32 v63, v63
	v_exp_f32_e32 v65, v65
	v_exp_f32_e32 v59, v59
	v_exp_f32_e32 v61, v61
	v_add_f32_e32 v62, 1.0, v62
	v_add_f32_e32 v64, 1.0, v64
	v_add_f32_e32 v66, 1.0, v58
	v_add_f32_e32 v67, 1.0, v60
	v_add_f32_e32 v63, 1.0, v63
	v_add_f32_e32 v65, 1.0, v65
	v_add_f32_e32 v72, 1.0, v59
	v_add_f32_e32 v61, 1.0, v61
	v_rcp_f32_e32 v58, v62
	v_rcp_f32_e32 v60, v64
	v_rcp_f32_e32 v59, v66
	v_rcp_f32_e32 v62, v63
	v_rcp_f32_e32 v63, v72
	v_rcp_f32_e32 v64, v65
	v_rcp_f32_e32 v65, v61
	v_rcp_f32_e32 v61, v67
	v_pk_mul_f32 v[56:57], v[56:57], v[62:63]
	v_pk_mul_f32 v[54:55], v[54:55], v[58:59]
	v_pk_mul_f32 v[52:53], v[52:53], v[64:65]
	v_pk_mul_f32 v[50:51], v[50:51], v[60:61]
	s_cbranch_vccnz .LBB0_172
	global_load_dwordx4 v[58:61], v[70:71], off offset:512
	global_load_dwordx4 v[62:65], v[70:71], off offset:528
	s_waitcnt vmcnt(0)
	v_pk_add_f32 v[56:57], v[56:57], v[60:61]
	v_pk_add_f32 v[54:55], v[54:55], v[58:59]
	v_pk_add_f32 v[52:53], v[52:53], v[64:65]
	v_pk_add_f32 v[50:51], v[50:51], v[62:63]

; __device__ __forceinline__ float sigm(float x) { return rcpf_(1.f + __expf(-x)); }
; __device__ __forceinline__ void unpack8(u32x4 w, float* e) { e[0] = lo_bf(w.x); e[1] = hi_bf(w.x); e[2] = lo_bf(w.y); e[3] = hi_bf(w.y); e[4] = lo_bf(w.z); e[5] = hi_bf(w.z); e[6] = lo_bf(w.w); e[7] = hi_bf(w.w); }
;     __device__ __forceinline__ void operator()(const f32x4 (&acc)[2][2][4][2], const Unit& u, int wr, int wc, int fr, int fq) const {
;     ...
;                 const int row = row0 + ai * 128 + m * 16;
; #pragma unroll
;                 for (int bj = 0; bj < 2; ++bj) {
;                     const int col = colt + bj * 128;
;                     const u32x4 gw = *(const u32x4*)(P + (size_t)row * NIN + C_GM + u.z * 1024 + col);
;                     float gt[8]; unpack8(gw, gt);
;                     f32x4 v0 = acc[ai][bj][m][0], v1 = acc[ai][bj][m][1];
; #pragma unroll
;                     for (int j = 0; j < 4; ++j) { v0[j] *= sigm(gt[j]); v1[j] *= sigm(gt[4 + j]); }
;                     float* tp = tmp + (size_t)row * 1024 + col;
;                     if (u.z > 0) { v0 += *(const f32x4*)tp; v1 += *(const f32x4*)(tp + 4); }
;                     if (u.z < 2) { *(f32x4*)tp = v0; *(f32x4*)(tp + 4) = v1; }
.LBB0_176:
	s_nop 1
	v_add_u32_e32 v52, 0x90, v142
	v_mov_b64_e32 v[50:51], s[12:13]
	v_mad_i64_i32 v[50:51], s[44:45], v52, s43, v[50:51]
	v_lshl_add_u64 v[50:51], s[38:39], 1, v[50:51]
	v_lshl_add_u64 v[50:51], v[140:141], 1, v[50:51]
	v_add_co_u32_e32 v54, vcc, 0x4000, v50
	v_ashrrev_i32_e32 v53, 31, v52
	s_nop 0
	v_addc_co_u32_e32 v55, vcc, 0, v51, vcc
	v_mov_b32_e32 v54, v178
	v_mov_b32_e32 v55, v179
	v_mov_b32_e32 v56, v180
	v_mov_b32_e32 v57, v181
	s_and_b64 vcc, exec, s[6:7]
	v_lshlrev_b32_e32 v60, 16, v55
	v_and_b32_e32 v61, 0xffff0000, v55
	v_lshlrev_b32_e32 v55, 16, v56
	v_mul_f32_e32 v55, 0xbfb8aa3b, v55
	v_exp_f32_e32 v55, v55
	v_lshlrev_b32_e32 v58, 16, v54
	v_and_b32_e32 v59, 0xffff0000, v54
	v_and_b32_e32 v62, 0xffff0000, v56
	v_add_f32_e32 v55, 1.0, v55
	v_mul_f32_e32 v54, 0xbfb8aa3b, v58
	v_rcp_f32_e32 v56, v55
	v_mul_f32_e32 v55, 0xbfb8aa3b, v59
	v_exp_f32_e32 v54, v54
	v_exp_f32_e32 v55, v55
	v_lshlrev_b32_e32 v63, 16, v57
	v_mul_f32_e32 v59, 0xbfb8aa3b, v63
	v_add_f32_e32 v54, 1.0, v54
	v_add_f32_e32 v55, 1.0, v55
	v_exp_f32_e32 v59, v59
	v_rcp_f32_e32 v54, v54
	v_rcp_f32_e32 v55, v55
	v_and_b32_e32 v64, 0xffff0000, v57
	v_add_f32_e32 v59, 1.0, v59
	v_mul_f32_e32 v57, 0xbfb8aa3b, v62
	v_mul_f32_e32 v58, 0xbfb8aa3b, v60
	v_rcp_f32_e32 v60, v59
	v_mul_f32_e32 v59, 0xbfb8aa3b, v61
	v_pk_mul_f32 v[46:47], v[46:47], v[54:55]
	v_mul_f32_e32 v54, 0xbfb8aa3b, v64
	v_exp_f32_e32 v57, v57
	v_exp_f32_e32 v58, v58
	v_exp_f32_e32 v59, v59
	v_exp_f32_e32 v54, v54
	v_add_f32_e32 v57, 1.0, v57
	v_add_f32_e32 v58, 1.0, v58
	v_add_f32_e32 v59, 1.0, v59
	v_add_f32_e32 v54, 1.0, v54
	v_rcp_f32_e32 v57, v57
	v_rcp_f32_e32 v58, v58
	v_rcp_f32_e32 v59, v59
	v_rcp_f32_e32 v61, v54
	v_lshlrev_b64 v[54:55], 12, v[52:53]
	v_lshl_add_u64 v[54:55], s[16:17], 0, v[54:55]
	v_pk_mul_f32 v[48:49], v[48:49], v[58:59]
	v_pk_mul_f32 v[44:45], v[44:45], v[60:61]
	v_pk_mul_f32 v[42:43], v[42:43], v[56:57]
	v_lshl_add_u64 v[54:55], v[140:141], 2, v[54:55]
	s_cbranch_vccnz .LBB0_178
	global_load_dwordx4 v[56:59], v[54:55], off
	global_load_dwordx4 v[60:63], v[54:55], off offset:16
	s_waitcnt vmcnt(0)
	v_pk_add_f32 v[48:49], v[48:49], v[58:59]
	v_pk_add_f32 v[46:47], v[46:47], v[56:57]
	v_pk_add_f32 v[44:45], v[44:45], v[62:63]
	v_pk_add_f32 v[42:43], v[42:43], v[60:61]

; __device__ __forceinline__ float sigm(float x) { return rcpf_(1.f + __expf(-x)); }
; __device__ __forceinline__ void unpack8(u32x4 w, float* e) { e[0] = lo_bf(w.x); e[1] = hi_bf(w.x); e[2] = lo_bf(w.y); e[3] = hi_bf(w.y); e[4] = lo_bf(w.z); e[5] = hi_bf(w.z); e[6] = lo_bf(w.w); e[7] = hi_bf(w.w); }
;     __device__ __forceinline__ void operator()(const f32x4 (&acc)[2][2][4][2], const Unit& u, int wr, int wc, int fr, int fq) const {
;     ...
;                 const int row = row0 + ai * 128 + m * 16;
; #pragma unroll
;                 for (int bj = 0; bj < 2; ++bj) {
;                     const int col = colt + bj * 128;
;                     const u32x4 gw = *(const u32x4*)(P + (size_t)row * NIN + C_GM + u.z * 1024 + col);
;                     float gt[8]; unpack8(gw, gt);
;                     f32x4 v0 = acc[ai][bj][m][0], v1 = acc[ai][bj][m][1];
; #pragma unroll
;                     for (int j = 0; j < 4; ++j) { v0[j] *= sigm(gt[j]); v1[j] *= sigm(gt[4 + j]); }
;                     float* tp = tmp + (size_t)row * 1024 + col;
;                     if (u.z > 0) { v0 += *(const f32x4*)tp; v1 += *(const f32x4*)(tp + 4); }
;                     if (u.z < 2) { *(f32x4*)tp = v0; *(f32x4*)(tp + 4) = v1; }
.LBB0_182:
	s_mov_b64 s[44:45], 0x4000
	s_nop 0
	v_lshl_add_u64 v[42:43], v[50:51], 0, s[44:45]
	v_mov_b32_e32 v42, v230
	v_mov_b32_e32 v43, v231
	v_mov_b32_e32 v44, v232
	v_mov_b32_e32 v45, v233
	s_and_b64 vcc, exec, s[6:7]
	v_lshlrev_b32_e32 v46, 16, v42
	v_and_b32_e32 v42, 0xffff0000, v42
	v_lshlrev_b32_e32 v47, 16, v43
	v_and_b32_e32 v43, 0xffff0000, v43
	v_lshlrev_b32_e32 v48, 16, v44
	v_and_b32_e32 v44, 0xffff0000, v44
	v_lshlrev_b32_e32 v49, 16, v45
	v_and_b32_e32 v45, 0xffff0000, v45
	v_mul_f32_e32 v46, 0xbfb8aa3b, v46
	v_mul_f32_e32 v48, 0xbfb8aa3b, v48
	v_mul_f32_e32 v42, 0xbfb8aa3b, v42
	v_mul_f32_e32 v44, 0xbfb8aa3b, v44
	v_mul_f32_e32 v47, 0xbfb8aa3b, v47
	v_mul_f32_e32 v49, 0xbfb8aa3b, v49
	v_mul_f32_e32 v43, 0xbfb8aa3b, v43
	v_mul_f32_e32 v45, 0xbfb8aa3b, v45
	v_exp_f32_e32 v46, v46
	v_exp_f32_e32 v48, v48
	v_exp_f32_e32 v42, v42
	v_exp_f32_e32 v44, v44
	v_exp_f32_e32 v47, v47
	v_exp_f32_e32 v49, v49
	v_exp_f32_e32 v43, v43
	v_exp_f32_e32 v45, v45
	v_add_f32_e32 v46, 1.0, v46
	v_add_f32_e32 v48, 1.0, v48
	v_add_f32_e32 v50, 1.0, v42
	v_add_f32_e32 v51, 1.0, v44
	v_add_f32_e32 v47, 1.0, v47
	v_add_f32_e32 v49, 1.0, v49
	v_add_f32_e32 v56, 1.0, v43
	v_add_f32_e32 v45, 1.0, v45
	v_rcp_f32_e32 v42, v46
	v_rcp_f32_e32 v44, v48
	v_rcp_f32_e32 v43, v50
	v_rcp_f32_e32 v46, v47
	v_rcp_f32_e32 v47, v56
	v_rcp_f32_e32 v48, v49
	v_rcp_f32_e32 v49, v45
	v_rcp_f32_e32 v45, v51
	v_pk_mul_f32 v[40:41], v[40:41], v[46:47]
	v_pk_mul_f32 v[38:39], v[38:39], v[42:43]
	v_pk_mul_f32 v[36:37], v[36:37], v[48:49]
	v_pk_mul_f32 v[34:35], v[34:35], v[44:45]
	s_cbranch_vccnz .LBB0_184
	global_load_dwordx4 v[42:45], v[54:55], off offset:512
	global_load_dwordx4 v[46:49], v[54:55], off offset:528
	s_waitcnt vmcnt(0)
	v_pk_add_f32 v[40:41], v[40:41], v[44:45]
	v_pk_add_f32 v[38:39], v[38:39], v[42:43]
	v_pk_add_f32 v[36:37], v[36:37], v[48:49]
	v_pk_add_f32 v[34:35], v[34:35], v[46:47]

; __device__ __forceinline__ float sigm(float x) { return rcpf_(1.f + __expf(-x)); }
; __device__ __forceinline__ void unpack8(u32x4 w, float* e) { e[0] = lo_bf(w.x); e[1] = hi_bf(w.x); e[2] = lo_bf(w.y); e[3] = hi_bf(w.y); e[4] = lo_bf(w.z); e[5] = hi_bf(w.z); e[6] = lo_bf(w.w); e[7] = hi_bf(w.w); }
;     __device__ __forceinline__ void operator()(const f32x4 (&acc)[2][2][4][2], const Unit& u, int wr, int wc, int fr, int fq) const {
;     ...
;                 const int row = row0 + ai * 128 + m * 16;
; #pragma unroll
;                 for (int bj = 0; bj < 2; ++bj) {
;                     const int col = colt + bj * 128;
;                     const u32x4 gw = *(const u32x4*)(P + (size_t)row * NIN + C_GM + u.z * 1024 + col);
;                     float gt[8]; unpack8(gw, gt);
;                     f32x4 v0 = acc[ai][bj][m][0], v1 = acc[ai][bj][m][1];
; #pragma unroll
;                     for (int j = 0; j < 4; ++j) { v0[j] *= sigm(gt[j]); v1[j] *= sigm(gt[4 + j]); }
;                     float* tp = tmp + (size_t)row * 1024 + col;
;                     if (u.z > 0) { v0 += *(const f32x4*)tp; v1 += *(const f32x4*)(tp + 4); }
;                     if (u.z < 2) { *(f32x4*)tp = v0; *(f32x4*)(tp + 4) = v1; }
.LBB0_188:
	s_nop 1
	v_add_u32_e32 v36, 0xa0, v142
	v_mov_b64_e32 v[34:35], s[12:13]
	v_mad_i64_i32 v[34:35], s[44:45], v36, s43, v[34:35]
	v_lshl_add_u64 v[34:35], s[38:39], 1, v[34:35]
	v_lshl_add_u64 v[34:35], v[140:141], 1, v[34:35]
	v_add_co_u32_e32 v38, vcc, 0x4000, v34
	v_ashrrev_i32_e32 v37, 31, v36
	s_nop 0
	v_addc_co_u32_e32 v39, vcc, 0, v35, vcc
	v_mov_b32_e32 v38, v188
	v_mov_b32_e32 v39, v189
	v_mov_b32_e32 v40, v190
	v_mov_b32_e32 v41, v191
	s_and_b64 vcc, exec, s[6:7]
	v_lshlrev_b32_e32 v44, 16, v39
	v_and_b32_e32 v45, 0xffff0000, v39
	v_lshlrev_b32_e32 v39, 16, v40
	v_mul_f32_e32 v39, 0xbfb8aa3b, v39
	v_exp_f32_e32 v39, v39
	v_lshlrev_b32_e32 v42, 16, v38
	v_and_b32_e32 v43, 0xffff0000, v38
	v_and_b32_e32 v46, 0xffff0000, v40
	v_add_f32_e32 v39, 1.0, v39
	v_mul_f32_e32 v38, 0xbfb8aa3b, v42
	v_rcp_f32_e32 v40, v39
	v_mul_f32_e32 v39, 0xbfb8aa3b, v43
	v_exp_f32_e32 v38, v38
	v_exp_f32_e32 v39, v39
	v_lshlrev_b32_e32 v47, 16, v41
	v_mul_f32_e32 v43, 0xbfb8aa3b, v47
	v_add_f32_e32 v38, 1.0, v38
	v_add_f32_e32 v39, 1.0, v39
	v_exp_f32_e32 v43, v43
	v_rcp_f32_e32 v38, v38
	v_rcp_f32_e32 v39, v39
	v_and_b32_e32 v48, 0xffff0000, v41
	v_add_f32_e32 v43, 1.0, v43
	v_mul_f32_e32 v41, 0xbfb8aa3b, v46
	v_mul_f32_e32 v42, 0xbfb8aa3b, v44
	v_rcp_f32_e32 v44, v43
	v_mul_f32_e32 v43, 0xbfb8aa3b, v45
	v_pk_mul_f32 v[30:31], v[30:31], v[38:39]
	v_mul_f32_e32 v38, 0xbfb8aa3b, v48
	v_exp_f32_e32 v41, v41
	v_exp_f32_e32 v42, v42
	v_exp_f32_e32 v43, v43
	v_exp_f32_e32 v38, v38
	v_add_f32_e32 v41, 1.0, v41
	v_add_f32_e32 v42, 1.0, v42
	v_add_f32_e32 v43, 1.0, v43
	v_add_f32_e32 v38, 1.0, v38
	v_rcp_f32_e32 v41, v41
	v_rcp_f32_e32 v42, v42
	v_rcp_f32_e32 v43, v43
	v_rcp_f32_e32 v45, v38
	v_lshlrev_b64 v[38:39], 12, v[36:37]
	v_lshl_add_u64 v[38:39], s[16:17], 0, v[38:39]
	v_pk_mul_f32 v[32:33], v[32:33], v[42:43]
	v_pk_mul_f32 v[28:29], v[28:29], v[44:45]
	v_pk_mul_f32 v[26:27], v[26:27], v[40:41]
	v_lshl_add_u64 v[38:39], v[140:141], 2, v[38:39]
	s_cbranch_vccnz .LBB0_190
	global_load_dwordx4 v[40:43], v[38:39], off
	global_load_dwordx4 v[44:47], v[38:39], off offset:16
	s_waitcnt vmcnt(0)
	v_pk_add_f32 v[32:33], v[32:33], v[42:43]
	v_pk_add_f32 v[30:31], v[30:31], v[40:41]
	v_pk_add_f32 v[28:29], v[28:29], v[46:47]
	v_pk_add_f32 v[26:27], v[26:27], v[44:45]

; __device__ __forceinline__ float sigm(float x) { return rcpf_(1.f + __expf(-x)); }
; __device__ __forceinline__ void unpack8(u32x4 w, float* e) { e[0] = lo_bf(w.x); e[1] = hi_bf(w.x); e[2] = lo_bf(w.y); e[3] = hi_bf(w.y); e[4] = lo_bf(w.z); e[5] = hi_bf(w.z); e[6] = lo_bf(w.w); e[7] = hi_bf(w.w); }
;     __device__ __forceinline__ void operator()(const f32x4 (&acc)[2][2][4][2], const Unit& u, int wr, int wc, int fr, int fq) const {
;     ...
;                 const int row = row0 + ai * 128 + m * 16;
; #pragma unroll
;                 for (int bj = 0; bj < 2; ++bj) {
;                     const int col = colt + bj * 128;
;                     const u32x4 gw = *(const u32x4*)(P + (size_t)row * NIN + C_GM + u.z * 1024 + col);
;                     float gt[8]; unpack8(gw, gt);
;                     f32x4 v0 = acc[ai][bj][m][0], v1 = acc[ai][bj][m][1];
; #pragma unroll
;                     for (int j = 0; j < 4; ++j) { v0[j] *= sigm(gt[j]); v1[j] *= sigm(gt[4 + j]); }
;                     float* tp = tmp + (size_t)row * 1024 + col;
;                     if (u.z > 0) { v0 += *(const f32x4*)tp; v1 += *(const f32x4*)(tp + 4); }
;                     if (u.z < 2) { *(f32x4*)tp = v0; *(f32x4*)(tp + 4) = v1; }
.LBB0_194:
	s_mov_b64 s[44:45], 0x4000
	s_nop 0
	v_lshl_add_u64 v[26:27], v[34:35], 0, s[44:45]
	v_mov_b32_e32 v26, v248
	v_mov_b32_e32 v27, v249
	v_mov_b32_e32 v28, v250
	v_mov_b32_e32 v29, v251
	s_and_b64 vcc, exec, s[6:7]
	v_lshlrev_b32_e32 v30, 16, v26
	v_and_b32_e32 v26, 0xffff0000, v26
	v_lshlrev_b32_e32 v31, 16, v27
	v_and_b32_e32 v27, 0xffff0000, v27
	v_lshlrev_b32_e32 v32, 16, v28
	v_and_b32_e32 v28, 0xffff0000, v28
	v_lshlrev_b32_e32 v33, 16, v29
	v_and_b32_e32 v29, 0xffff0000, v29
	v_mul_f32_e32 v30, 0xbfb8aa3b, v30
	v_mul_f32_e32 v32, 0xbfb8aa3b, v32
	v_mul_f32_e32 v26, 0xbfb8aa3b, v26
	v_mul_f32_e32 v28, 0xbfb8aa3b, v28
	v_mul_f32_e32 v31, 0xbfb8aa3b, v31
	v_mul_f32_e32 v33, 0xbfb8aa3b, v33
	v_mul_f32_e32 v27, 0xbfb8aa3b, v27
	v_mul_f32_e32 v29, 0xbfb8aa3b, v29
	v_exp_f32_e32 v30, v30
	v_exp_f32_e32 v32, v32
	v_exp_f32_e32 v26, v26
	v_exp_f32_e32 v28, v28
	v_exp_f32_e32 v31, v31
	v_exp_f32_e32 v33, v33
	v_exp_f32_e32 v27, v27
	v_exp_f32_e32 v29, v29
	v_add_f32_e32 v30, 1.0, v30
	v_add_f32_e32 v32, 1.0, v32
	v_add_f32_e32 v34, 1.0, v26
	v_add_f32_e32 v35, 1.0, v28
	v_add_f32_e32 v31, 1.0, v31
	v_add_f32_e32 v33, 1.0, v33
	v_add_f32_e32 v40, 1.0, v27
	v_add_f32_e32 v29, 1.0, v29
	v_rcp_f32_e32 v26, v30
	v_rcp_f32_e32 v28, v32
	v_rcp_f32_e32 v27, v34
	v_rcp_f32_e32 v30, v31
	v_rcp_f32_e32 v31, v40
	v_rcp_f32_e32 v32, v33
	v_rcp_f32_e32 v33, v29
	v_rcp_f32_e32 v29, v35
	v_pk_mul_f32 v[24:25], v[24:25], v[30:31]
	v_pk_mul_f32 v[22:23], v[22:23], v[26:27]
	v_pk_mul_f32 v[20:21], v[20:21], v[32:33]
	v_pk_mul_f32 v[18:19], v[18:19], v[28:29]
	s_cbranch_vccnz .LBB0_196
	global_load_dwordx4 v[26:29], v[38:39], off offset:512
	global_load_dwordx4 v[30:33], v[38:39], off offset:528
	s_waitcnt vmcnt(0)
	v_pk_add_f32 v[24:25], v[24:25], v[28:29]
	v_pk_add_f32 v[22:23], v[22:23], v[26:27]
	v_pk_add_f32 v[20:21], v[20:21], v[32:33]
	v_pk_add_f32 v[18:19], v[18:19], v[30:31]

; __device__ __forceinline__ float sigm(float x) { return rcpf_(1.f + __expf(-x)); }
; __device__ __forceinline__ void unpack8(u32x4 w, float* e) { e[0] = lo_bf(w.x); e[1] = hi_bf(w.x); e[2] = lo_bf(w.y); e[3] = hi_bf(w.y); e[4] = lo_bf(w.z); e[5] = hi_bf(w.z); e[6] = lo_bf(w.w); e[7] = hi_bf(w.w); }
;     __device__ __forceinline__ void operator()(const f32x4 (&acc)[2][2][4][2], const Unit& u, int wr, int wc, int fr, int fq) const {
;     ...
;                 const int row = row0 + ai * 128 + m * 16;
; #pragma unroll
;                 for (int bj = 0; bj < 2; ++bj) {
;                     const int col = colt + bj * 128;
;                     const u32x4 gw = *(const u32x4*)(P + (size_t)row * NIN + C_GM + u.z * 1024 + col);
;                     float gt[8]; unpack8(gw, gt);
;                     f32x4 v0 = acc[ai][bj][m][0], v1 = acc[ai][bj][m][1];
; #pragma unroll
;                     for (int j = 0; j < 4; ++j) { v0[j] *= sigm(gt[j]); v1[j] *= sigm(gt[4 + j]); }
;                     float* tp = tmp + (size_t)row * 1024 + col;
;                     if (u.z > 0) { v0 += *(const f32x4*)tp; v1 += *(const f32x4*)(tp + 4); }
;                     if (u.z < 2) { *(f32x4*)tp = v0; *(f32x4*)(tp + 4) = v1; }
.LBB0_200:
	s_nop 1
	v_add_u32_e32 v20, 0xb0, v142
	v_mov_b64_e32 v[18:19], s[12:13]
	v_mad_i64_i32 v[18:19], s[44:45], v20, s43, v[18:19]
	v_lshl_add_u64 v[18:19], s[38:39], 1, v[18:19]
	v_lshl_add_u64 v[18:19], v[140:141], 1, v[18:19]
	v_add_co_u32_e32 v22, vcc, 0x4000, v18
	v_ashrrev_i32_e32 v21, 31, v20
	s_nop 0
	v_addc_co_u32_e32 v23, vcc, 0, v19, vcc
	v_mov_b32_e32 v22, v192
	v_mov_b32_e32 v23, v193
	v_mov_b32_e32 v24, v194
	v_mov_b32_e32 v25, v195
	s_and_b64 vcc, exec, s[6:7]
	v_lshlrev_b32_e32 v28, 16, v23
	v_and_b32_e32 v29, 0xffff0000, v23
	v_lshlrev_b32_e32 v23, 16, v24
	v_mul_f32_e32 v23, 0xbfb8aa3b, v23
	v_exp_f32_e32 v23, v23
	v_lshlrev_b32_e32 v26, 16, v22
	v_and_b32_e32 v27, 0xffff0000, v22
	v_and_b32_e32 v30, 0xffff0000, v24
	v_add_f32_e32 v23, 1.0, v23
	v_mul_f32_e32 v22, 0xbfb8aa3b, v26
	v_rcp_f32_e32 v24, v23
	v_mul_f32_e32 v23, 0xbfb8aa3b, v27
	v_exp_f32_e32 v22, v22
	v_exp_f32_e32 v23, v23
	v_lshlrev_b32_e32 v31, 16, v25
	v_mul_f32_e32 v27, 0xbfb8aa3b, v31
	v_add_f32_e32 v22, 1.0, v22
	v_add_f32_e32 v23, 1.0, v23
	v_exp_f32_e32 v27, v27
	v_rcp_f32_e32 v22, v22
	v_rcp_f32_e32 v23, v23
	v_and_b32_e32 v32, 0xffff0000, v25
	v_add_f32_e32 v27, 1.0, v27
	v_mul_f32_e32 v25, 0xbfb8aa3b, v30
	v_mul_f32_e32 v26, 0xbfb8aa3b, v28
	v_rcp_f32_e32 v28, v27
	v_mul_f32_e32 v27, 0xbfb8aa3b, v29
	v_pk_mul_f32 v[14:15], v[14:15], v[22:23]
	v_mul_f32_e32 v22, 0xbfb8aa3b, v32
	v_exp_f32_e32 v25, v25
	v_exp_f32_e32 v26, v26
	v_exp_f32_e32 v27, v27
	v_exp_f32_e32 v22, v22
	v_add_f32_e32 v25, 1.0, v25
	v_add_f32_e32 v26, 1.0, v26
	v_add_f32_e32 v27, 1.0, v27
	v_add_f32_e32 v22, 1.0, v22
	v_rcp_f32_e32 v25, v25
	v_rcp_f32_e32 v26, v26
	v_rcp_f32_e32 v27, v27
	v_rcp_f32_e32 v29, v22
	v_lshlrev_b64 v[22:23], 12, v[20:21]
	v_lshl_add_u64 v[22:23], s[16:17], 0, v[22:23]
	v_pk_mul_f32 v[16:17], v[16:17], v[26:27]
	v_pk_mul_f32 v[12:13], v[12:13], v[28:29]
	v_pk_mul_f32 v[10:11], v[10:11], v[24:25]
	v_lshl_add_u64 v[22:23], v[140:141], 2, v[22:23]
	s_cbranch_vccnz .LBB0_202
	global_load_dwordx4 v[24:27], v[22:23], off
	global_load_dwordx4 v[28:31], v[22:23], off offset:16
	s_waitcnt vmcnt(0)
	v_pk_add_f32 v[16:17], v[16:17], v[26:27]
	v_pk_add_f32 v[14:15], v[14:15], v[24:25]
	v_pk_add_f32 v[12:13], v[12:13], v[30:31]
	v_pk_add_f32 v[10:11], v[10:11], v[28:29]

; __device__ __forceinline__ unsigned cvt_pk_bf16(float lo, float hi) { unsigned r; asm("v_cvt_pk_bf16_f32 %0, %1, %2" : "=v"(r) : "v"(lo), "v"(hi)); return r; }
;     __device__ __forceinline__ void operator()(const f32x4 (&acc)[2][2][4][2], const Unit& u, int wr, int wc, int fr, int fq) const {
;         const int row0 = u.pm * 256 + wr * 64 + fr, colt = u.pn * 256 + wc * 32 + 8 * fq;
; #pragma unroll
;         for (int ai = 0; ai < 2; ++ai)
; #pragma unroll
;             for (int m = 0; m < 4; ++m) {
;                 const int row = row0 + ai * 128 + m * 16; float ss = 0.f;
; #pragma unroll
;                 for (int bj = 0; bj < 2; ++bj) {
;                     const int col = colt + bj * 128; float* xp = X + (size_t)row * 1024 + col; const float* xi = Xin + (size_t)row * 1024 + col;
;                     const f32x4 v0 = acc[ai][bj][m][0] + *(const f32x4*)xi, v1 = acc[ai][bj][m][1] + *(const f32x4*)(xi + 4);
;                     *(f32x4*)xp = v0; *(f32x4*)(xp + 4) = v1;
;                     u32x4 w; w.x = cvt_pk_bf16(v0[0], v0[1]); w.y = cvt_pk_bf16(v0[2], v0[3]); w.z = cvt_pk_bf16(v1[0], v1[1]); w.w = cvt_pk_bf16(v1[2], v1[3]);
;                     *(u32x4*)(Xb + (size_t)row * 1024 + col) = w;
;                     ss += (v0[0] * v0[0] + v0[1] * v0[1]) + (v0[2] * v0[2] + v0[3] * v0[3]) + (v1[0] * v1[0] + v1[1] * v1[1]) + (v1[2] * v1[2] + v1[3] * v1[3]);
;                 }
;                 ss += __shfl_xor(ss, 16); ss += __shfl_xor(ss, 32);
;                 if (fq == 0) atomicAdd(sumsq + row, ss);
.LBB0_776:
	v_lshl_add_u32 v144, s87, 8, v146
	v_lshl_or_b32 v140, s86, 8, v148
	v_ashrrev_i32_e32 v145, 31, v144
	v_lshlrev_b64 v[150:151], 12, v[144:145]
	v_ashrrev_i32_e32 v141, 31, v140
	v_lshl_add_u64 v[152:153], s[16:17], 0, v[150:151]
	v_lshlrev_b64 v[142:143], 2, v[140:141]
	v_lshl_add_u64 v[150:151], s[26:27], 0, v[150:151]
	v_lshl_add_u64 v[160:161], v[150:151], 0, v[142:143]
	v_lshl_add_u64 v[158:159], v[152:153], 0, v[142:143]
	s_mov_b32 s99, 0
	global_load_dwordx4 v[248:251], v[160:161], off offset:528
	global_load_dwordx4 v[230:233], v[160:161], off offset:512
	s_mov_b32 s98, 0x10000
	v_lshl_add_u64 v[162:163], v[160:161], 0, s[98:99]
	global_load_dwordx4 v[166:169], v[162:163], off offset:16
	global_load_dwordx4 v[170:173], v[162:163], off offset:512
	global_load_dwordx4 v[174:177], v[162:163], off offset:528
	global_load_dwordx4 v[162:165], v[162:163], off
	s_mov_b32 s98, 0x20000
	v_lshl_add_u64 v[178:179], v[160:161], 0, s[98:99]
	global_load_dwordx4 v[188:191], v[178:179], off offset:16
	global_load_dwordx4 v[192:195], v[178:179], off offset:512
	global_load_dwordx4 v[196:199], v[178:179], off offset:528
	global_load_dwordx4 v[178:181], v[178:179], off
	s_mov_b32 s98, 0x30000
	v_lshl_add_u64 v[200:201], v[160:161], 0, s[98:99]
	global_load_dwordx4 v[204:207], v[200:201], off offset:16
	global_load_dwordx4 v[208:211], v[200:201], off offset:512
	global_load_dwordx4 v[212:215], v[200:201], off offset:528
	global_load_dwordx4 v[200:203], v[200:201], off
	global_load_dwordx4 v[150:153], v[160:161], off offset:16
	global_load_dwordx4 v[154:157], v[160:161], off
	s_waitcnt vmcnt(0)
	v_pk_add_f32 v[128:129], v[128:129], v[152:153]
	v_pk_add_f32 v[124:125], v[124:125], v[156:157]
	v_pk_add_f32 v[122:123], v[122:123], v[154:155]
	v_pk_add_f32 v[126:127], v[126:127], v[150:151]
	global_store_dwordx4 v[158:159], v[122:125], off
	global_store_dwordx4 v[158:159], v[126:129], off offset:16
	v_cvt_pk_bf16_f32 v150, v122, v123
	v_lshlrev_b64 v[154:155], 11, v[144:145]
	v_mul_f32_e32 v123, v123, v123
	v_fmac_f32_e32 v123, v122, v122
	v_mul_f32_e32 v122, v125, v125
	v_fmac_f32_e32 v122, v124, v124
	v_add_f32_e32 v122, v123, v122
	v_mul_f32_e32 v123, v127, v127
	v_lshl_add_u64 v[154:155], s[18:19], 0, v[154:155]
	v_fmac_f32_e32 v123, v126, v126
	v_lshl_add_u64 v[154:155], v[140:141], 1, v[154:155]
	v_add_f32_e32 v122, v122, v123
	v_mul_f32_e32 v123, v129, v129
	v_cvt_pk_bf16_f32 v151, v124, v125
	v_cvt_pk_bf16_f32 v152, v126, v127
	v_cvt_pk_bf16_f32 v153, v128, v129
	global_store_dwordx4 v[154:155], v[150:153], off
	v_fmac_f32_e32 v123, v128, v128
	s_nop 0
	v_add_f32_e32 v150, v123, v122
	s_nop 1
	v_mov_b32_e32 v122, v248
	v_mov_b32_e32 v123, v249
	v_mov_b32_e32 v124, v250
	v_mov_b32_e32 v125, v251
	s_nop 1
	v_mov_b32_e32 v126, v230
	v_mov_b32_e32 v127, v231
	v_mov_b32_e32 v128, v232
	v_mov_b32_e32 v129, v233
	v_pk_add_f32 v[116:117], v[116:117], v[124:125]
	v_pk_add_f32 v[120:121], v[120:121], v[128:129]
	v_pk_add_f32 v[118:119], v[118:119], v[126:127]
	v_pk_add_f32 v[114:115], v[114:115], v[122:123]
	global_store_dwordx4 v[158:159], v[118:121], off offset:512
	global_store_dwordx4 v[158:159], v[114:117], off offset:528
	v_cvt_pk_bf16_f32 v122, v118, v119
	v_cvt_pk_bf16_f32 v124, v114, v115
	v_cvt_pk_bf16_f32 v125, v116, v117
	v_cvt_pk_bf16_f32 v123, v120, v121
	s_nop 0
	v_mul_f32_e32 v119, v119, v119
	v_fmac_f32_e32 v119, v118, v118
	v_mul_f32_e32 v118, v121, v121
	v_fmac_f32_e32 v118, v120, v120
	v_mul_f32_e32 v115, v115, v115
	v_add_f32_e32 v118, v119, v118
	v_fmac_f32_e32 v115, v114, v114
	v_add_f32_e32 v114, v118, v115
	v_mul_f32_e32 v115, v117, v117
	v_fmac_f32_e32 v115, v116, v116
	v_and_b32_e32 v116, 64, v240
	v_add_f32_e32 v114, v115, v114
	v_xor_b32_e32 v115, 16, v240
	v_add_u32_e32 v117, 64, v116
	v_cmp_lt_i32_e32 vcc, v115, v117
	v_add_f32_e32 v114, v150, v114
	global_store_dwordx4 v[154:155], v[122:125], off offset:256
	v_cndmask_b32_e32 v115, v240, v115, vcc
	v_lshlrev_b32_e32 v116, 2, v115
	ds_bpermute_b32 v115, v116, v114
	s_waitcnt lgkmcnt(0)
	v_add_f32_e32 v118, v114, v115
	v_xor_b32_e32 v114, 32, v240
	v_cmp_lt_i32_e32 vcc, v114, v117
	s_nop 1
	v_cndmask_b32_e32 v114, v240, v114, vcc
	v_lshlrev_b32_e32 v117, 2, v114
	ds_bpermute_b32 v119, v117, v118
	v_lshl_add_u64 v[114:115], v[144:145], 2, s[22:23]
	s_and_saveexec_b64 s[38:39], s[6:7]
	s_cbranch_execz .LBB0_778
	s_waitcnt lgkmcnt(0)
	v_add_f32_e32 v118, v118, v119
	global_atomic_add_f32 v[114:115], v118, off
; __device__ __forceinline__ unsigned cvt_pk_bf16(float lo, float hi) { unsigned r; asm("v_cvt_pk_bf16_f32 %0, %1, %2" : "=v"(r) : "v"(lo), "v"(hi)); return r; }
;     __device__ __forceinline__ void operator()(const f32x4 (&acc)[2][2][4][2], const Unit& u, int wr, int wc, int fr, int fq) const {
;     ...
;                 const int row = row0 + ai * 128 + m * 16; float ss = 0.f;
; #pragma unroll
;                 for (int bj = 0; bj < 2; ++bj) {
;                     const int col = colt + bj * 128; float* xp = X + (size_t)row * 1024 + col; const float* xi = Xin + (size_t)row * 1024 + col;
;                     const f32x4 v0 = acc[ai][bj][m][0] + *(const f32x4*)xi, v1 = acc[ai][bj][m][1] + *(const f32x4*)(xi + 4);
;                     *(f32x4*)xp = v0; *(f32x4*)(xp + 4) = v1;
;                     u32x4 w; w.x = cvt_pk_bf16(v0[0], v0[1]); w.y = cvt_pk_bf16(v0[2], v0[3]); w.z = cvt_pk_bf16(v1[0], v1[1]); w.w = cvt_pk_bf16(v1[2], v1[3]);
;                     *(u32x4*)(Xb + (size_t)row * 1024 + col) = w;
;                     ss += (v0[0] * v0[0] + v0[1] * v0[1]) + (v0[2] * v0[2] + v0[3] * v0[3]) + (v1[0] * v1[0] + v1[1] * v1[1]) + (v1[2] * v1[2] + v1[3] * v1[3]);
;                 }
;                 ss += __shfl_xor(ss, 16); ss += __shfl_xor(ss, 32);
;                 if (fq == 0) atomicAdd(sumsq + row, ss);
.LBB0_778:
	s_or_b64 exec, exec, s[38:39]
	v_or_b32_e32 v126, 16, v144
	v_ashrrev_i32_e32 v127, 31, v126
	v_lshlrev_b64 v[128:129], 12, v[126:127]
	s_waitcnt lgkmcnt(0)
	v_lshl_add_u64 v[118:119], s[26:27], 0, v[128:129]
	v_lshl_add_u64 v[150:151], v[118:119], 0, v[142:143]
	s_nop 1
	v_mov_b32_e32 v118, v162
	v_mov_b32_e32 v119, v163
	v_mov_b32_e32 v120, v164
	v_mov_b32_e32 v121, v165
	s_nop 1
	v_mov_b32_e32 v122, v166
	v_mov_b32_e32 v123, v167
	v_mov_b32_e32 v124, v168
	v_mov_b32_e32 v125, v169
	v_lshlrev_b64 v[126:127], 11, v[126:127]
	v_lshl_add_u64 v[128:129], s[16:17], 0, v[128:129]
	v_lshl_add_u64 v[126:127], s[18:19], 0, v[126:127]
	v_lshl_add_u64 v[128:129], v[128:129], 0, v[142:143]
	v_lshl_add_u64 v[126:127], v[140:141], 1, v[126:127]
	v_pk_add_f32 v[112:113], v[112:113], v[120:121]
	v_pk_add_f32 v[110:111], v[110:111], v[118:119]
	v_pk_add_f32 v[108:109], v[108:109], v[124:125]
	v_pk_add_f32 v[106:107], v[106:107], v[122:123]
	global_store_dwordx4 v[128:129], v[110:113], off
	global_store_dwordx4 v[128:129], v[106:109], off offset:16
	v_cvt_pk_bf16_f32 v118, v110, v111
	v_cvt_pk_bf16_f32 v119, v112, v113
	v_cvt_pk_bf16_f32 v120, v106, v107
	v_cvt_pk_bf16_f32 v121, v108, v109
	global_store_dwordx4 v[126:127], v[118:121], off
	s_nop 1
	v_mov_b32_e32 v118, v170
	v_mov_b32_e32 v119, v171
	v_mov_b32_e32 v120, v172
	v_mov_b32_e32 v121, v173
	s_nop 0
	s_nop 1
	v_mov_b32_e32 v122, v174
	v_mov_b32_e32 v123, v175
	v_mov_b32_e32 v124, v176
	v_mov_b32_e32 v125, v177
	v_mul_f32_e32 v111, v111, v111
	v_mul_f32_e32 v113, v113, v113
	v_mul_f32_e32 v107, v107, v107
	v_fmac_f32_e32 v111, v110, v110
	v_fmac_f32_e32 v113, v112, v112
	v_mul_f32_e32 v109, v109, v109
	v_fmac_f32_e32 v107, v106, v106
	v_add_f32_e32 v106, v111, v113
	v_fmac_f32_e32 v109, v108, v108
	v_add_f32_e32 v106, v106, v107
	v_add_f32_e32 v110, v109, v106
	v_pk_add_f32 v[104:105], v[104:105], v[120:121]
	v_pk_add_f32 v[102:103], v[102:103], v[118:119]
	v_pk_add_f32 v[106:107], v[98:99], v[122:123]
	v_mul_f32_e32 v98, v103, v103
	v_mul_f32_e32 v99, v105, v105
	v_pk_add_f32 v[108:109], v[100:101], v[124:125]
	v_mul_f32_e32 v100, v107, v107
	v_fmac_f32_e32 v98, v102, v102
	v_fmac_f32_e32 v99, v104, v104
	v_mul_f32_e32 v101, v109, v109
	v_fmac_f32_e32 v100, v106, v106
	v_add_f32_e32 v98, v98, v99
	v_add_f32_e32 v98, v98, v100
	v_fmac_f32_e32 v101, v108, v108
	v_add_f32_e32 v98, v101, v98
	v_add_f32_e32 v98, v110, v98
	ds_bpermute_b32 v99, v116, v98
	global_store_dwordx4 v[128:129], v[102:105], off offset:512
	global_store_dwordx4 v[128:129], v[106:109], off offset:528
	v_cvt_pk_bf16_f32 v100, v102, v103
	v_cvt_pk_bf16_f32 v101, v104, v105
	s_waitcnt lgkmcnt(0)
	v_add_f32_e32 v98, v98, v99
	ds_bpermute_b32 v99, v117, v98
	v_cvt_pk_bf16_f32 v102, v106, v107
	v_cvt_pk_bf16_f32 v103, v108, v109
	global_store_dwordx4 v[126:127], v[100:103], off offset:256
	s_and_saveexec_b64 s[38:39], s[6:7]
	s_cbranch_execz .LBB0_780
	s_waitcnt lgkmcnt(0)
	v_add_f32_e32 v98, v98, v99
	global_atomic_add_f32 v[114:115], v98, off offset:64
.LBB0_780:
	s_or_b64 exec, exec, s[38:39]
	v_or_b32_e32 v106, 32, v144
	v_ashrrev_i32_e32 v107, 31, v106
	v_lshlrev_b64 v[108:109], 12, v[106:107]
	s_waitcnt lgkmcnt(0)
	v_lshl_add_u64 v[98:99], s[26:27], 0, v[108:109]
	v_lshl_add_u64 v[110:111], v[98:99], 0, v[142:143]
	s_nop 1
	v_mov_b32_e32 v98, v178
	v_mov_b32_e32 v99, v179
	v_mov_b32_e32 v100, v180
	v_mov_b32_e32 v101, v181
	s_nop 1
	v_mov_b32_e32 v102, v188
	v_mov_b32_e32 v103, v189
	v_mov_b32_e32 v104, v190
	v_mov_b32_e32 v105, v191
	v_lshlrev_b64 v[106:107], 11, v[106:107]
	v_lshl_add_u64 v[108:109], s[16:17], 0, v[108:109]
	v_lshl_add_u64 v[106:107], s[18:19], 0, v[106:107]
	v_lshl_add_u64 v[108:109], v[108:109], 0, v[142:143]
	v_lshl_add_u64 v[106:107], v[140:141], 1, v[106:107]
	v_pk_add_f32 v[96:97], v[96:97], v[100:101]
	v_pk_add_f32 v[94:95], v[94:95], v[98:99]
	v_pk_add_f32 v[92:93], v[92:93], v[104:105]
	v_pk_add_f32 v[90:91], v[90:91], v[102:103]
	global_store_dwordx4 v[108:109], v[94:97], off
	global_store_dwordx4 v[108:109], v[90:93], off offset:16
	v_cvt_pk_bf16_f32 v98, v94, v95
	v_cvt_pk_bf16_f32 v99, v96, v97
	v_cvt_pk_bf16_f32 v100, v90, v91
	v_cvt_pk_bf16_f32 v101, v92, v93
	global_store_dwordx4 v[106:107], v[98:101], off
	s_nop 1
	v_mov_b32_e32 v98, v192
	v_mov_b32_e32 v99, v193
	v_mov_b32_e32 v100, v194
	v_mov_b32_e32 v101, v195
	s_nop 0
	s_nop 1
	v_mov_b32_e32 v102, v196
	v_mov_b32_e32 v103, v197
	v_mov_b32_e32 v104, v198
	v_mov_b32_e32 v105, v199
	v_mul_f32_e32 v95, v95, v95
	v_mul_f32_e32 v97, v97, v97
	v_mul_f32_e32 v91, v91, v91
	v_fmac_f32_e32 v95, v94, v94
	v_fmac_f32_e32 v97, v96, v96
	v_mul_f32_e32 v93, v93, v93
	v_fmac_f32_e32 v91, v90, v90
	v_add_f32_e32 v90, v95, v97
	v_fmac_f32_e32 v93, v92, v92
	v_add_f32_e32 v90, v90, v91
	v_add_f32_e32 v94, v93, v90
	v_pk_add_f32 v[88:89], v[88:89], v[100:101]
	v_pk_add_f32 v[86:87], v[86:87], v[98:99]
	v_pk_add_f32 v[90:91], v[82:83], v[102:103]
	v_mul_f32_e32 v82, v87, v87
	v_mul_f32_e32 v83, v89, v89
	v_pk_add_f32 v[92:93], v[84:85], v[104:105]
	v_mul_f32_e32 v84, v91, v91
	v_fmac_f32_e32 v82, v86, v86
	v_fmac_f32_e32 v83, v88, v88
	v_mul_f32_e32 v85, v93, v93
	v_fmac_f32_e32 v84, v90, v90
	v_add_f32_e32 v82, v82, v83
	v_add_f32_e32 v82, v82, v84
	v_fmac_f32_e32 v85, v92, v92
	v_add_f32_e32 v82, v85, v82
	v_add_f32_e32 v82, v94, v82
	ds_bpermute_b32 v83, v116, v82
	global_store_dwordx4 v[108:109], v[86:89], off offset:512
	global_store_dwordx4 v[108:109], v[90:93], off offset:528
	v_cvt_pk_bf16_f32 v84, v86, v87
	v_cvt_pk_bf16_f32 v85, v88, v89
	s_waitcnt lgkmcnt(0)
	v_add_f32_e32 v82, v82, v83
	ds_bpermute_b32 v83, v117, v82
	v_cvt_pk_bf16_f32 v86, v90, v91
	v_cvt_pk_bf16_f32 v87, v92, v93
	global_store_dwordx4 v[106:107], v[84:87], off offset:256
	s_and_saveexec_b64 s[38:39], s[6:7]
	s_cbranch_execz .LBB0_782
	s_waitcnt lgkmcnt(0)
	v_add_f32_e32 v82, v82, v83
	global_atomic_add_f32 v[114:115], v82, off offset:128
; __device__ __forceinline__ unsigned cvt_pk_bf16(float lo, float hi) { unsigned r; asm("v_cvt_pk_bf16_f32 %0, %1, %2" : "=v"(r) : "v"(lo), "v"(hi)); return r; }
;     __device__ __forceinline__ void operator()(const f32x4 (&acc)[2][2][4][2], const Unit& u, int wr, int wc, int fr, int fq) const {
;     ...
;                 const int row = row0 + ai * 128 + m * 16; float ss = 0.f;
; #pragma unroll
;                 for (int bj = 0; bj < 2; ++bj) {
;                     const int col = colt + bj * 128; float* xp = X + (size_t)row * 1024 + col; const float* xi = Xin + (size_t)row * 1024 + col;
;                     const f32x4 v0 = acc[ai][bj][m][0] + *(const f32x4*)xi, v1 = acc[ai][bj][m][1] + *(const f32x4*)(xi + 4);
;                     *(f32x4*)xp = v0; *(f32x4*)(xp + 4) = v1;
;                     u32x4 w; w.x = cvt_pk_bf16(v0[0], v0[1]); w.y = cvt_pk_bf16(v0[2], v0[3]); w.z = cvt_pk_bf16(v1[0], v1[1]); w.w = cvt_pk_bf16(v1[2], v1[3]);
;                     *(u32x4*)(Xb + (size_t)row * 1024 + col) = w;
;                     ss += (v0[0] * v0[0] + v0[1] * v0[1]) + (v0[2] * v0[2] + v0[3] * v0[3]) + (v1[0] * v1[0] + v1[1] * v1[1]) + (v1[2] * v1[2] + v1[3] * v1[3]);
;                 }
;                 ss += __shfl_xor(ss, 16); ss += __shfl_xor(ss, 32);
;                 if (fq == 0) atomicAdd(sumsq + row, ss);
.LBB0_782:
	s_or_b64 exec, exec, s[38:39]
	v_or_b32_e32 v90, 48, v144
	v_ashrrev_i32_e32 v91, 31, v90
	v_lshlrev_b64 v[92:93], 12, v[90:91]
	s_waitcnt lgkmcnt(0)
	v_lshl_add_u64 v[82:83], s[26:27], 0, v[92:93]
	v_lshl_add_u64 v[94:95], v[82:83], 0, v[142:143]
	s_nop 1
	v_mov_b32_e32 v82, v200
	v_mov_b32_e32 v83, v201
	v_mov_b32_e32 v84, v202
	v_mov_b32_e32 v85, v203
	s_nop 1
	v_mov_b32_e32 v86, v204
	v_mov_b32_e32 v87, v205
	v_mov_b32_e32 v88, v206
	v_mov_b32_e32 v89, v207
	v_lshlrev_b64 v[90:91], 11, v[90:91]
	v_lshl_add_u64 v[92:93], s[16:17], 0, v[92:93]
	v_lshl_add_u64 v[90:91], s[18:19], 0, v[90:91]
	v_lshl_add_u64 v[92:93], v[92:93], 0, v[142:143]
	v_lshl_add_u64 v[90:91], v[140:141], 1, v[90:91]
	v_pk_add_f32 v[80:81], v[80:81], v[84:85]
	v_pk_add_f32 v[78:79], v[78:79], v[82:83]
	v_pk_add_f32 v[76:77], v[76:77], v[88:89]
	v_pk_add_f32 v[74:75], v[74:75], v[86:87]
	global_store_dwordx4 v[92:93], v[78:81], off
	global_store_dwordx4 v[92:93], v[74:77], off offset:16
	v_cvt_pk_bf16_f32 v82, v78, v79
	v_cvt_pk_bf16_f32 v83, v80, v81
	v_cvt_pk_bf16_f32 v84, v74, v75
	v_cvt_pk_bf16_f32 v85, v76, v77
	global_store_dwordx4 v[90:91], v[82:85], off
	s_nop 1
	v_mov_b32_e32 v82, v208
	v_mov_b32_e32 v83, v209
	v_mov_b32_e32 v84, v210
	v_mov_b32_e32 v85, v211
	s_nop 0
	s_nop 1
	v_mov_b32_e32 v86, v212
	v_mov_b32_e32 v87, v213
	v_mov_b32_e32 v88, v214
	v_mov_b32_e32 v89, v215
	v_mul_f32_e32 v79, v79, v79
	v_mul_f32_e32 v81, v81, v81
	v_mul_f32_e32 v75, v75, v75
	v_fmac_f32_e32 v79, v78, v78
	v_fmac_f32_e32 v81, v80, v80
	v_mul_f32_e32 v77, v77, v77
	v_fmac_f32_e32 v75, v74, v74
	v_add_f32_e32 v74, v79, v81
	v_fmac_f32_e32 v77, v76, v76
	v_add_f32_e32 v74, v74, v75
	v_add_f32_e32 v78, v77, v74
	v_pk_add_f32 v[72:73], v[72:73], v[84:85]
	v_pk_add_f32 v[70:71], v[70:71], v[82:83]
	v_pk_add_f32 v[74:75], v[66:67], v[86:87]
	v_mul_f32_e32 v66, v71, v71
	v_mul_f32_e32 v67, v73, v73
	v_pk_add_f32 v[76:77], v[68:69], v[88:89]
	v_mul_f32_e32 v68, v75, v75
	v_fmac_f32_e32 v66, v70, v70
	v_fmac_f32_e32 v67, v72, v72
	v_mul_f32_e32 v69, v77, v77
	v_fmac_f32_e32 v68, v74, v74
	v_add_f32_e32 v66, v66, v67
	v_add_f32_e32 v66, v66, v68
	v_fmac_f32_e32 v69, v76, v76
	v_add_f32_e32 v66, v69, v66
	v_add_f32_e32 v66, v78, v66
	ds_bpermute_b32 v67, v116, v66
	global_store_dwordx4 v[92:93], v[70:73], off offset:512
	global_store_dwordx4 v[92:93], v[74:77], off offset:528
	v_cvt_pk_bf16_f32 v68, v70, v71
	v_cvt_pk_bf16_f32 v69, v72, v73
	s_waitcnt lgkmcnt(0)
	v_add_f32_e32 v66, v66, v67
	ds_bpermute_b32 v67, v117, v66
	v_cvt_pk_bf16_f32 v70, v74, v75
	v_cvt_pk_bf16_f32 v71, v76, v77
	global_store_dwordx4 v[90:91], v[68:71], off offset:256
	s_and_saveexec_b64 s[38:39], s[6:7]
	s_cbranch_execz .LBB0_784
	s_waitcnt lgkmcnt(0)
	v_add_f32_e32 v66, v66, v67
	global_atomic_add_f32 v[114:115], v66, off offset:192
.LBB0_784:
	s_or_b64 exec, exec, s[38:39]
	v_add_u32_e32 v74, 0x80, v144
	v_ashrrev_i32_e32 v75, 31, v74
	v_lshlrev_b64 v[76:77], 12, v[74:75]
	s_waitcnt lgkmcnt(0)
	v_lshl_add_u64 v[66:67], s[26:27], 0, v[76:77]
	v_lshl_add_u64 v[78:79], v[66:67], 0, v[142:143]
	s_mov_b32 s99, 0
	global_load_dwordx4 v[230:233], v[78:79], off offset:512
	global_load_dwordx4 v[248:251], v[78:79], off offset:528
	s_mov_b32 s98, 0x10000
	v_lshl_add_u64 v[162:163], v[78:79], 0, s[98:99]
	global_load_dwordx4 v[166:169], v[162:163], off offset:16
	global_load_dwordx4 v[170:173], v[162:163], off offset:512
	global_load_dwordx4 v[174:177], v[162:163], off offset:528
	global_load_dwordx4 v[162:165], v[162:163], off
	s_mov_b32 s98, 0x20000
	v_lshl_add_u64 v[178:179], v[78:79], 0, s[98:99]
	global_load_dwordx4 v[188:191], v[178:179], off offset:16
	global_load_dwordx4 v[192:195], v[178:179], off offset:512
	global_load_dwordx4 v[196:199], v[178:179], off offset:528
	global_load_dwordx4 v[178:181], v[178:179], off
	s_mov_b32 s98, 0x30000
	v_lshl_add_u64 v[200:201], v[78:79], 0, s[98:99]
	global_load_dwordx4 v[204:207], v[200:201], off offset:16
	global_load_dwordx4 v[208:211], v[200:201], off offset:512
	global_load_dwordx4 v[212:215], v[200:201], off offset:528
	global_load_dwordx4 v[200:203], v[200:201], off
	global_load_dwordx4 v[66:69], v[78:79], off
	global_load_dwordx4 v[70:73], v[78:79], off offset:16
	v_lshlrev_b64 v[74:75], 11, v[74:75]
	v_lshl_add_u64 v[76:77], s[16:17], 0, v[76:77]
	v_lshl_add_u64 v[74:75], s[18:19], 0, v[74:75]
	v_lshl_add_u64 v[76:77], v[76:77], 0, v[142:143]
	v_lshl_add_u64 v[74:75], v[140:141], 1, v[74:75]
	s_waitcnt vmcnt(1)
	v_pk_add_f32 v[64:65], v[64:65], v[68:69]
	v_pk_add_f32 v[62:63], v[62:63], v[66:67]
	s_waitcnt vmcnt(0)
	v_pk_add_f32 v[60:61], v[60:61], v[72:73]
	v_pk_add_f32 v[58:59], v[58:59], v[70:71]
	global_store_dwordx4 v[76:77], v[62:65], off
	global_store_dwordx4 v[76:77], v[58:61], off offset:16
	v_cvt_pk_bf16_f32 v66, v62, v63
	v_cvt_pk_bf16_f32 v67, v64, v65
	v_cvt_pk_bf16_f32 v68, v58, v59
	v_cvt_pk_bf16_f32 v69, v60, v61
	global_store_dwordx4 v[74:75], v[66:69], off
	s_nop 1
	v_mov_b32_e32 v66, v230
	v_mov_b32_e32 v67, v231
	v_mov_b32_e32 v68, v232
	v_mov_b32_e32 v69, v233
	s_nop 0
	s_nop 1
	v_mov_b32_e32 v70, v248
	v_mov_b32_e32 v71, v249
	v_mov_b32_e32 v72, v250
	v_mov_b32_e32 v73, v251
	v_mul_f32_e32 v63, v63, v63
	v_mul_f32_e32 v65, v65, v65
	v_mul_f32_e32 v59, v59, v59
	v_fmac_f32_e32 v63, v62, v62
	v_fmac_f32_e32 v65, v64, v64
	v_mul_f32_e32 v61, v61, v61
	v_fmac_f32_e32 v59, v58, v58
	v_add_f32_e32 v58, v63, v65
	v_fmac_f32_e32 v61, v60, v60
	v_add_f32_e32 v58, v58, v59
	v_add_f32_e32 v62, v61, v58
	v_pk_add_f32 v[56:57], v[56:57], v[68:69]
	v_pk_add_f32 v[54:55], v[54:55], v[66:67]
	v_pk_add_f32 v[58:59], v[50:51], v[70:71]
	v_mul_f32_e32 v50, v55, v55
	v_mul_f32_e32 v51, v57, v57
	v_pk_add_f32 v[60:61], v[52:53], v[72:73]
	v_mul_f32_e32 v52, v59, v59
	v_fmac_f32_e32 v50, v54, v54
	v_fmac_f32_e32 v51, v56, v56
	v_mul_f32_e32 v53, v61, v61
	v_fmac_f32_e32 v52, v58, v58
	v_add_f32_e32 v50, v50, v51
	v_add_f32_e32 v50, v50, v52
	v_fmac_f32_e32 v53, v60, v60
	v_add_f32_e32 v50, v53, v50
	v_add_f32_e32 v50, v62, v50
	ds_bpermute_b32 v51, v116, v50
	global_store_dwordx4 v[76:77], v[54:57], off offset:512
	global_store_dwordx4 v[76:77], v[58:61], off offset:528
	v_cvt_pk_bf16_f32 v52, v54, v55
	v_cvt_pk_bf16_f32 v53, v56, v57
	s_waitcnt lgkmcnt(0)
	v_add_f32_e32 v50, v50, v51
	ds_bpermute_b32 v51, v117, v50
	v_cvt_pk_bf16_f32 v54, v58, v59
	v_cvt_pk_bf16_f32 v55, v60, v61
	global_store_dwordx4 v[74:75], v[52:55], off offset:256
	s_and_saveexec_b64 s[38:39], s[6:7]
	s_cbranch_execz .LBB0_786
	s_waitcnt lgkmcnt(0)
	v_add_f32_e32 v50, v50, v51
	global_atomic_add_f32 v[114:115], v50, off offset:512
; __device__ __forceinline__ unsigned cvt_pk_bf16(float lo, float hi) { unsigned r; asm("v_cvt_pk_bf16_f32 %0, %1, %2" : "=v"(r) : "v"(lo), "v"(hi)); return r; }
;     __device__ __forceinline__ void operator()(const f32x4 (&acc)[2][2][4][2], const Unit& u, int wr, int wc, int fr, int fq) const {
;     ...
;                 const int row = row0 + ai * 128 + m * 16; float ss = 0.f;
; #pragma unroll
;                 for (int bj = 0; bj < 2; ++bj) {
;                     const int col = colt + bj * 128; float* xp = X + (size_t)row * 1024 + col; const float* xi = Xin + (size_t)row * 1024 + col;
;                     const f32x4 v0 = acc[ai][bj][m][0] + *(const f32x4*)xi, v1 = acc[ai][bj][m][1] + *(const f32x4*)(xi + 4);
;                     *(f32x4*)xp = v0; *(f32x4*)(xp + 4) = v1;
;                     u32x4 w; w.x = cvt_pk_bf16(v0[0], v0[1]); w.y = cvt_pk_bf16(v0[2], v0[3]); w.z = cvt_pk_bf16(v1[0], v1[1]); w.w = cvt_pk_bf16(v1[2], v1[3]);
;                     *(u32x4*)(Xb + (size_t)row * 1024 + col) = w;
;                     ss += (v0[0] * v0[0] + v0[1] * v0[1]) + (v0[2] * v0[2] + v0[3] * v0[3]) + (v1[0] * v1[0] + v1[1] * v1[1]) + (v1[2] * v1[2] + v1[3] * v1[3]);
;                 }
;                 ss += __shfl_xor(ss, 16); ss += __shfl_xor(ss, 32);
;                 if (fq == 0) atomicAdd(sumsq + row, ss);
.LBB0_786:
	s_or_b64 exec, exec, s[38:39]
	v_add_u32_e32 v58, 0x90, v144
	v_ashrrev_i32_e32 v59, 31, v58
	v_lshlrev_b64 v[60:61], 12, v[58:59]
	s_waitcnt lgkmcnt(0)
	v_lshl_add_u64 v[50:51], s[26:27], 0, v[60:61]
	v_lshl_add_u64 v[62:63], v[50:51], 0, v[142:143]
	s_nop 1
	v_mov_b32_e32 v50, v162
	v_mov_b32_e32 v51, v163
	v_mov_b32_e32 v52, v164
	v_mov_b32_e32 v53, v165
	s_nop 1
	v_mov_b32_e32 v54, v166
	v_mov_b32_e32 v55, v167
	v_mov_b32_e32 v56, v168
	v_mov_b32_e32 v57, v169
	v_lshlrev_b64 v[58:59], 11, v[58:59]
	v_lshl_add_u64 v[60:61], s[16:17], 0, v[60:61]
	v_lshl_add_u64 v[58:59], s[18:19], 0, v[58:59]
	v_lshl_add_u64 v[60:61], v[60:61], 0, v[142:143]
	v_lshl_add_u64 v[58:59], v[140:141], 1, v[58:59]
	v_pk_add_f32 v[48:49], v[48:49], v[52:53]
	v_pk_add_f32 v[46:47], v[46:47], v[50:51]
	v_pk_add_f32 v[44:45], v[44:45], v[56:57]
	v_pk_add_f32 v[42:43], v[42:43], v[54:55]
	global_store_dwordx4 v[60:61], v[46:49], off
	global_store_dwordx4 v[60:61], v[42:45], off offset:16
	v_cvt_pk_bf16_f32 v50, v46, v47
	v_cvt_pk_bf16_f32 v51, v48, v49
	v_cvt_pk_bf16_f32 v52, v42, v43
	v_cvt_pk_bf16_f32 v53, v44, v45
	global_store_dwordx4 v[58:59], v[50:53], off
	s_nop 1
	v_mov_b32_e32 v50, v170
	v_mov_b32_e32 v51, v171
	v_mov_b32_e32 v52, v172
	v_mov_b32_e32 v53, v173
	s_nop 0
	s_nop 1
	v_mov_b32_e32 v54, v174
	v_mov_b32_e32 v55, v175
	v_mov_b32_e32 v56, v176
	v_mov_b32_e32 v57, v177
	v_mul_f32_e32 v47, v47, v47
	v_mul_f32_e32 v49, v49, v49
	v_mul_f32_e32 v43, v43, v43
	v_fmac_f32_e32 v47, v46, v46
	v_fmac_f32_e32 v49, v48, v48
	v_mul_f32_e32 v45, v45, v45
	v_fmac_f32_e32 v43, v42, v42
	v_add_f32_e32 v42, v47, v49
	v_fmac_f32_e32 v45, v44, v44
	v_add_f32_e32 v42, v42, v43
	v_add_f32_e32 v46, v45, v42
	v_pk_add_f32 v[40:41], v[40:41], v[52:53]
	v_pk_add_f32 v[38:39], v[38:39], v[50:51]
	v_pk_add_f32 v[42:43], v[34:35], v[54:55]
	v_mul_f32_e32 v34, v39, v39
	v_mul_f32_e32 v35, v41, v41
	v_pk_add_f32 v[44:45], v[36:37], v[56:57]
	v_mul_f32_e32 v36, v43, v43
	v_fmac_f32_e32 v34, v38, v38
	v_fmac_f32_e32 v35, v40, v40
	v_mul_f32_e32 v37, v45, v45
	v_fmac_f32_e32 v36, v42, v42
	v_add_f32_e32 v34, v34, v35
	v_add_f32_e32 v34, v34, v36
	v_fmac_f32_e32 v37, v44, v44
	v_add_f32_e32 v34, v37, v34
	v_add_f32_e32 v34, v46, v34
	ds_bpermute_b32 v35, v116, v34
	global_store_dwordx4 v[60:61], v[38:41], off offset:512
	global_store_dwordx4 v[60:61], v[42:45], off offset:528
	v_cvt_pk_bf16_f32 v36, v38, v39
	v_cvt_pk_bf16_f32 v37, v40, v41
	s_waitcnt lgkmcnt(0)
	v_add_f32_e32 v34, v34, v35
	ds_bpermute_b32 v35, v117, v34
	v_cvt_pk_bf16_f32 v38, v42, v43
	v_cvt_pk_bf16_f32 v39, v44, v45
	global_store_dwordx4 v[58:59], v[36:39], off offset:256
	s_and_saveexec_b64 s[38:39], s[6:7]
	s_cbranch_execz .LBB0_788
	s_waitcnt lgkmcnt(0)
	v_add_f32_e32 v34, v34, v35
	global_atomic_add_f32 v[114:115], v34, off offset:576
; __device__ __forceinline__ unsigned cvt_pk_bf16(float lo, float hi) { unsigned r; asm("v_cvt_pk_bf16_f32 %0, %1, %2" : "=v"(r) : "v"(lo), "v"(hi)); return r; }
;     __device__ __forceinline__ void operator()(const f32x4 (&acc)[2][2][4][2], const Unit& u, int wr, int wc, int fr, int fq) const {
;     ...
;                 const int row = row0 + ai * 128 + m * 16; float ss = 0.f;
; #pragma unroll
;                 for (int bj = 0; bj < 2; ++bj) {
;                     const int col = colt + bj * 128; float* xp = X + (size_t)row * 1024 + col; const float* xi = Xin + (size_t)row * 1024 + col;
;                     const f32x4 v0 = acc[ai][bj][m][0] + *(const f32x4*)xi, v1 = acc[ai][bj][m][1] + *(const f32x4*)(xi + 4);
;                     *(f32x4*)xp = v0; *(f32x4*)(xp + 4) = v1;
;                     u32x4 w; w.x = cvt_pk_bf16(v0[0], v0[1]); w.y = cvt_pk_bf16(v0[2], v0[3]); w.z = cvt_pk_bf16(v1[0], v1[1]); w.w = cvt_pk_bf16(v1[2], v1[3]);
;                     *(u32x4*)(Xb + (size_t)row * 1024 + col) = w;
;                     ss += (v0[0] * v0[0] + v0[1] * v0[1]) + (v0[2] * v0[2] + v0[3] * v0[3]) + (v1[0] * v1[0] + v1[1] * v1[1]) + (v1[2] * v1[2] + v1[3] * v1[3]);
;                 }
;                 ss += __shfl_xor(ss, 16); ss += __shfl_xor(ss, 32);
;                 if (fq == 0) atomicAdd(sumsq + row, ss);
.LBB0_788:
	s_or_b64 exec, exec, s[38:39]
	v_add_u32_e32 v42, 0xa0, v144
	v_ashrrev_i32_e32 v43, 31, v42
	v_lshlrev_b64 v[44:45], 12, v[42:43]
	s_waitcnt lgkmcnt(0)
	v_lshl_add_u64 v[34:35], s[26:27], 0, v[44:45]
	v_lshl_add_u64 v[46:47], v[34:35], 0, v[142:143]
	s_nop 1
	v_mov_b32_e32 v34, v178
	v_mov_b32_e32 v35, v179
	v_mov_b32_e32 v36, v180
	v_mov_b32_e32 v37, v181
	s_nop 1
	v_mov_b32_e32 v38, v188
	v_mov_b32_e32 v39, v189
	v_mov_b32_e32 v40, v190
	v_mov_b32_e32 v41, v191
	v_lshlrev_b64 v[42:43], 11, v[42:43]
	v_lshl_add_u64 v[44:45], s[16:17], 0, v[44:45]
	v_lshl_add_u64 v[42:43], s[18:19], 0, v[42:43]
	v_lshl_add_u64 v[44:45], v[44:45], 0, v[142:143]
	v_lshl_add_u64 v[42:43], v[140:141], 1, v[42:43]
	v_pk_add_f32 v[32:33], v[32:33], v[36:37]
	v_pk_add_f32 v[30:31], v[30:31], v[34:35]
	v_pk_add_f32 v[28:29], v[28:29], v[40:41]
	v_pk_add_f32 v[26:27], v[26:27], v[38:39]
	global_store_dwordx4 v[44:45], v[30:33], off
	global_store_dwordx4 v[44:45], v[26:29], off offset:16
	v_cvt_pk_bf16_f32 v34, v30, v31
	v_cvt_pk_bf16_f32 v35, v32, v33
	v_cvt_pk_bf16_f32 v36, v26, v27
	v_cvt_pk_bf16_f32 v37, v28, v29
	global_store_dwordx4 v[42:43], v[34:37], off
	s_nop 1
	v_mov_b32_e32 v34, v192
	v_mov_b32_e32 v35, v193
	v_mov_b32_e32 v36, v194
	v_mov_b32_e32 v37, v195
	s_nop 0
	s_nop 1
	v_mov_b32_e32 v38, v196
	v_mov_b32_e32 v39, v197
	v_mov_b32_e32 v40, v198
	v_mov_b32_e32 v41, v199
	v_mul_f32_e32 v31, v31, v31
	v_mul_f32_e32 v33, v33, v33
	v_mul_f32_e32 v27, v27, v27
	v_fmac_f32_e32 v31, v30, v30
	v_fmac_f32_e32 v33, v32, v32
	v_mul_f32_e32 v29, v29, v29
	v_fmac_f32_e32 v27, v26, v26
	v_add_f32_e32 v26, v31, v33
	v_fmac_f32_e32 v29, v28, v28
	v_add_f32_e32 v26, v26, v27
	v_add_f32_e32 v30, v29, v26
	v_pk_add_f32 v[24:25], v[24:25], v[36:37]
	v_pk_add_f32 v[22:23], v[22:23], v[34:35]
	v_pk_add_f32 v[26:27], v[18:19], v[38:39]
	v_mul_f32_e32 v18, v23, v23
	v_mul_f32_e32 v19, v25, v25
	v_pk_add_f32 v[28:29], v[20:21], v[40:41]
	v_mul_f32_e32 v20, v27, v27
	v_fmac_f32_e32 v18, v22, v22
	v_fmac_f32_e32 v19, v24, v24
	v_mul_f32_e32 v21, v29, v29
	v_fmac_f32_e32 v20, v26, v26
	v_add_f32_e32 v18, v18, v19
	v_add_f32_e32 v18, v18, v20
	v_fmac_f32_e32 v21, v28, v28
	v_add_f32_e32 v18, v21, v18
	v_add_f32_e32 v18, v30, v18
	ds_bpermute_b32 v19, v116, v18
	global_store_dwordx4 v[44:45], v[22:25], off offset:512
	global_store_dwordx4 v[44:45], v[26:29], off offset:528
	v_cvt_pk_bf16_f32 v20, v22, v23
	v_cvt_pk_bf16_f32 v21, v24, v25
	s_waitcnt lgkmcnt(0)
	v_add_f32_e32 v18, v18, v19
	ds_bpermute_b32 v19, v117, v18
	v_cvt_pk_bf16_f32 v22, v26, v27
	v_cvt_pk_bf16_f32 v23, v28, v29
	global_store_dwordx4 v[42:43], v[20:23], off offset:256
	s_and_saveexec_b64 s[38:39], s[6:7]
	s_cbranch_execz .LBB0_790
	s_waitcnt lgkmcnt(0)
	v_add_f32_e32 v18, v18, v19
	global_atomic_add_f32 v[114:115], v18, off offset:640
.LBB0_790:
	s_or_b64 exec, exec, s[38:39]
	v_add_u32_e32 v28, 0xb0, v144
	v_ashrrev_i32_e32 v29, 31, v28
	v_lshlrev_b64 v[20:21], 12, v[28:29]
	s_waitcnt lgkmcnt(0)
	v_lshl_add_u64 v[18:19], s[16:17], 0, v[20:21]
	v_lshl_add_u64 v[20:21], s[26:27], 0, v[20:21]
	v_lshl_add_u64 v[30:31], v[20:21], 0, v[142:143]
	s_nop 1
	v_mov_b32_e32 v20, v204
	v_mov_b32_e32 v21, v205
	v_mov_b32_e32 v22, v206
	v_mov_b32_e32 v23, v207
	s_nop 1
	v_mov_b32_e32 v24, v200
	v_mov_b32_e32 v25, v201
	v_mov_b32_e32 v26, v202
	v_mov_b32_e32 v27, v203
	v_lshl_add_u64 v[18:19], v[18:19], 0, v[142:143]
	v_pk_add_f32 v[12:13], v[12:13], v[22:23]
	v_pk_add_f32 v[16:17], v[16:17], v[26:27]
	v_pk_add_f32 v[14:15], v[14:15], v[24:25]
	v_pk_add_f32 v[10:11], v[10:11], v[20:21]
	global_store_dwordx4 v[18:19], v[14:17], off
	global_store_dwordx4 v[18:19], v[10:13], off offset:16
	v_cvt_pk_bf16_f32 v20, v14, v15
	v_cvt_pk_bf16_f32 v22, v10, v11
	v_lshlrev_b64 v[24:25], 11, v[28:29]
	v_mul_f32_e32 v15, v15, v15
	v_fmac_f32_e32 v15, v14, v14
	v_mul_f32_e32 v14, v17, v17
	v_fmac_f32_e32 v14, v16, v16
	v_mul_f32_e32 v11, v11, v11
	v_lshl_add_u64 v[24:25], s[18:19], 0, v[24:25]
	v_add_f32_e32 v14, v15, v14
	v_fmac_f32_e32 v11, v10, v10
	v_lshl_add_u64 v[24:25], v[140:141], 1, v[24:25]
	v_add_f32_e32 v10, v14, v11
	v_mul_f32_e32 v11, v13, v13
	v_cvt_pk_bf16_f32 v21, v16, v17
	v_cvt_pk_bf16_f32 v23, v12, v13
	global_store_dwordx4 v[24:25], v[20:23], off
	v_fmac_f32_e32 v11, v12, v12
	s_nop 0
	v_add_f32_e32 v20, v11, v10
	s_nop 1
	v_mov_b32_e32 v10, v212
	v_mov_b32_e32 v11, v213
	v_mov_b32_e32 v12, v214
	v_mov_b32_e32 v13, v215
	s_nop 1
	v_mov_b32_e32 v14, v208
	v_mov_b32_e32 v15, v209
	v_mov_b32_e32 v16, v210
	v_mov_b32_e32 v17, v211
	v_pk_add_f32 v[2:3], v[2:3], v[12:13]
	v_pk_add_f32 v[8:9], v[8:9], v[16:17]
	v_pk_add_f32 v[6:7], v[6:7], v[14:15]
	v_pk_add_f32 v[0:1], v[0:1], v[10:11]
	global_store_dwordx4 v[18:19], v[6:9], off offset:512
	global_store_dwordx4 v[18:19], v[0:3], off offset:528
	v_cvt_pk_bf16_f32 v10, v6, v7
	v_cvt_pk_bf16_f32 v12, v0, v1
	v_cvt_pk_bf16_f32 v11, v8, v9
	v_cvt_pk_bf16_f32 v13, v2, v3
	s_nop 0
	v_mul_f32_e32 v7, v7, v7
	v_fmac_f32_e32 v7, v6, v6
	v_mul_f32_e32 v6, v9, v9
	v_fmac_f32_e32 v6, v8, v8
	v_mul_f32_e32 v1, v1, v1
	v_add_f32_e32 v6, v7, v6
	v_fmac_f32_e32 v1, v0, v0
	v_add_f32_e32 v0, v6, v1
	v_mul_f32_e32 v1, v3, v3
	v_fmac_f32_e32 v1, v2, v2
	v_add_f32_e32 v0, v1, v0
	v_add_f32_e32 v0, v20, v0
	ds_bpermute_b32 v1, v116, v0
	global_store_dwordx4 v[24:25], v[10:13], off offset:256
	s_waitcnt lgkmcnt(0)
	v_add_f32_e32 v0, v0, v1
	ds_bpermute_b32 v1, v117, v0
	s_and_saveexec_b64 s[38:39], s[6:7]
	s_cbranch_execz .LBB0_761
	s_waitcnt lgkmcnt(0)
	v_add_f32_e32 v0, v0, v1
	global_atomic_add_f32 v[114:115], v0, off offset:704
	s_branch .LBB0_761
